# panel exchange protocol: tagged 8-byte slots (value, value xor tag) polled directly by each row's lane; no store-ack wait, no counter atomic, no separate partial loads
# speedup vs baseline: 1.0099x; 1.0099x over previous
; __device__ __forceinline__ float xhalf_sum(float x) { auto t = __builtin_amdgcn_permlane32_swap(__float_as_uint(x), __float_as_uint(x), false, false); return __uint_as_float(t[0]) + __uint_as_float(t[1]); }
;     __device__ __forceinline__ void exchange(int e, float (&sv)[2][4], float (&rv)[2][4], const Unit& u, int wr, int wc, int fr, int fq, LAS unsigned char* lds, int wid, int lane) const {
;     ...
;                 float v = sv[ai][m];
;                 { auto t1 = __builtin_amdgcn_permlane16_swap(__float_as_uint(v), __float_as_uint(v), false, false); v = __uint_as_float(t1[0]) + __uint_as_float(t1[1]); }
;                 v = xhalf_sum(v);
;                 if (fq == 0) P[(ai * HALF + wr * 64 + m * 16 + fr) * 4 + wc] = v;
;     __device__ __forceinline__ void fused(f32x4 (&acc)[2][2][4][2], const Unit& u, int wr, int wc, int fr, int fq, LAS unsigned char* lds, int wid, int lane) const {
;     ...
;         for (int ai = 0; ai < 2; ++ai)
; #pragma unroll
;             for (int m = 0; m < 4; ++m) {
;                 float q = 0.f;
; #pragma unroll
;                 for (int bj = 0; bj < 2; ++bj)
; #pragma unroll
;                     for (int n = 0; n < 2; ++n) { const f32x4 x = acc[ai][bj][m][n]; q += (x[0] * x[0] + x[1] * x[1]) + (x[2] * x[2] + x[3] * x[3]); }
;                 sv[ai][m] = q;
;             }
;         exchange(0, sv, rv, u, wr, wc, fr, fq, lds, wid, lane);
.LBB0_1401:
	v_mul_f32_e32 v146, v127, v127
	v_mul_f32_e32 v147, v129, v129
	v_fmac_f32_e32 v146, v126, v126
	v_fmac_f32_e32 v147, v128, v128
	v_add_f32_e32 v146, v146, v147
	v_mul_f32_e32 v147, v123, v123
	v_mul_f32_e32 v148, v125, v125
	v_fmac_f32_e32 v147, v122, v122
	v_fmac_f32_e32 v148, v124, v124
	v_add_f32_e32 v147, v147, v148
	v_add_f32_e32 v146, v146, v147
	v_mul_f32_e32 v147, v119, v119
	v_mul_f32_e32 v148, v121, v121
	v_fmac_f32_e32 v147, v118, v118
	v_fmac_f32_e32 v148, v120, v120
	v_add_f32_e32 v147, v147, v148
	v_add_f32_e32 v146, v146, v147
	v_mul_f32_e32 v147, v115, v115
	v_mul_f32_e32 v148, v117, v117
	v_fmac_f32_e32 v147, v114, v114
	v_fmac_f32_e32 v148, v116, v116
	v_add_f32_e32 v147, v147, v148
	v_add_f32_e32 v146, v146, v147
	v_mov_b32_e32 v147, v146
	s_nop 1
	v_permlane16_swap_b32_e32 v146, v147
	v_add_f32_e32 v146, v146, v147
	v_mov_b32_e32 v147, v146
	s_nop 1
	v_permlane32_swap_b32_e32 v146, v147
	s_and_saveexec_b64 s[8:9], s[4:5]
	v_add_f32_e32 v146, v146, v147
	ds_write_b32 v212, v146
	s_or_b64 exec, exec, s[8:9]
	v_mul_f32_e32 v146, v111, v111
	v_mul_f32_e32 v147, v113, v113
	v_fmac_f32_e32 v146, v110, v110
	v_fmac_f32_e32 v147, v112, v112
	v_add_f32_e32 v146, v146, v147
	v_mul_f32_e32 v147, v107, v107
	v_mul_f32_e32 v148, v109, v109
	v_fmac_f32_e32 v147, v106, v106
	v_fmac_f32_e32 v148, v108, v108
	v_add_f32_e32 v147, v147, v148
	v_add_f32_e32 v146, v146, v147
	v_mul_f32_e32 v147, v103, v103
	v_mul_f32_e32 v148, v105, v105
	v_fmac_f32_e32 v147, v102, v102
	v_fmac_f32_e32 v148, v104, v104
	v_add_f32_e32 v147, v147, v148
	v_add_f32_e32 v146, v146, v147
	v_mul_f32_e32 v147, v99, v99
	v_mul_f32_e32 v148, v101, v101
	v_fmac_f32_e32 v147, v98, v98
	v_fmac_f32_e32 v148, v100, v100
	v_add_f32_e32 v147, v147, v148
	v_add_f32_e32 v146, v146, v147
	v_mov_b32_e32 v147, v146
	s_nop 1
	v_permlane16_swap_b32_e32 v146, v147
	v_add_f32_e32 v146, v146, v147
	v_mov_b32_e32 v147, v146
	s_nop 1
	v_permlane32_swap_b32_e32 v146, v147
	s_and_saveexec_b64 s[8:9], s[4:5]
	v_add_f32_e32 v146, v146, v147
	ds_write_b32 v212, v146 offset:256
	s_or_b64 exec, exec, s[8:9]
	v_mul_f32_e32 v146, v95, v95
	v_mul_f32_e32 v147, v97, v97
	v_fmac_f32_e32 v146, v94, v94
	v_fmac_f32_e32 v147, v96, v96
	v_add_f32_e32 v146, v146, v147
	v_mul_f32_e32 v147, v91, v91
	v_mul_f32_e32 v148, v93, v93
	v_fmac_f32_e32 v147, v90, v90
	v_fmac_f32_e32 v148, v92, v92
	v_add_f32_e32 v147, v147, v148
	v_add_f32_e32 v146, v146, v147
	v_mul_f32_e32 v147, v87, v87
	v_mul_f32_e32 v148, v89, v89
	v_fmac_f32_e32 v147, v86, v86
	v_fmac_f32_e32 v148, v88, v88
	v_add_f32_e32 v147, v147, v148
	v_add_f32_e32 v146, v146, v147
	v_mul_f32_e32 v147, v83, v83
	v_mul_f32_e32 v148, v85, v85
	v_fmac_f32_e32 v147, v82, v82
	v_fmac_f32_e32 v148, v84, v84
	v_add_f32_e32 v147, v147, v148
	v_add_f32_e32 v146, v146, v147
	v_mov_b32_e32 v147, v146
	s_nop 1
	v_permlane16_swap_b32_e32 v146, v147
	v_add_f32_e32 v146, v146, v147
	v_mov_b32_e32 v147, v146
	s_nop 1
	v_permlane32_swap_b32_e32 v146, v147
	s_and_saveexec_b64 s[8:9], s[4:5]
	v_add_f32_e32 v146, v146, v147
	ds_write_b32 v212, v146 offset:512
	s_or_b64 exec, exec, s[8:9]
	v_mul_f32_e32 v146, v79, v79
	v_mul_f32_e32 v147, v81, v81
	v_fmac_f32_e32 v146, v78, v78
	v_fmac_f32_e32 v147, v80, v80
	v_add_f32_e32 v146, v146, v147
	v_mul_f32_e32 v147, v75, v75
	v_mul_f32_e32 v148, v77, v77
	v_fmac_f32_e32 v147, v74, v74
	v_fmac_f32_e32 v148, v76, v76
	v_add_f32_e32 v147, v147, v148
	v_add_f32_e32 v146, v146, v147
	v_mul_f32_e32 v147, v71, v71
	v_mul_f32_e32 v148, v73, v73
	v_fmac_f32_e32 v147, v70, v70
	v_fmac_f32_e32 v148, v72, v72
	v_add_f32_e32 v147, v147, v148
	v_add_f32_e32 v146, v146, v147
	v_mul_f32_e32 v147, v67, v67
	v_mul_f32_e32 v148, v69, v69
	v_fmac_f32_e32 v147, v66, v66
	v_fmac_f32_e32 v148, v68, v68
	v_add_f32_e32 v147, v147, v148
	v_add_f32_e32 v146, v146, v147
	v_mov_b32_e32 v147, v146
	s_nop 1
	v_permlane16_swap_b32_e32 v146, v147
	v_add_f32_e32 v146, v146, v147
	v_mov_b32_e32 v147, v146
	s_nop 1
	v_permlane32_swap_b32_e32 v146, v147
	s_and_saveexec_b64 s[8:9], s[4:5]
	v_add_f32_e32 v146, v146, v147
	ds_write_b32 v212, v146 offset:768
	s_or_b64 exec, exec, s[8:9]
	v_mul_f32_e32 v146, v63, v63
	v_mul_f32_e32 v147, v65, v65
	v_fmac_f32_e32 v146, v62, v62
	v_fmac_f32_e32 v147, v64, v64
	v_add_f32_e32 v146, v146, v147
	v_mul_f32_e32 v147, v59, v59
	v_mul_f32_e32 v148, v61, v61
	v_fmac_f32_e32 v147, v58, v58
	v_fmac_f32_e32 v148, v60, v60
	v_add_f32_e32 v147, v147, v148
	v_add_f32_e32 v146, v146, v147
	v_mul_f32_e32 v147, v55, v55
	v_mul_f32_e32 v148, v57, v57
	v_fmac_f32_e32 v147, v54, v54
	v_fmac_f32_e32 v148, v56, v56
	v_add_f32_e32 v147, v147, v148
	v_add_f32_e32 v146, v146, v147
	v_mul_f32_e32 v147, v51, v51
	v_mul_f32_e32 v148, v53, v53
	v_fmac_f32_e32 v147, v50, v50
	v_fmac_f32_e32 v148, v52, v52
	v_add_f32_e32 v147, v147, v148
	v_add_f32_e32 v146, v146, v147
	v_mov_b32_e32 v147, v146
	s_nop 1
; #define LAS __attribute__((address_space(3)))
;     __device__ __forceinline__ void exchange(int e, float (&sv)[2][4], float (&rv)[2][4], const Unit& u, int wr, int wc, int fr, int fq, LAS unsigned char* lds, int wid, int lane) const {
;     ...
;                 if (fq == 0) P[(ai * HALF + wr * 64 + m * 16 + fr) * 4 + wc] = v;
;             }
;         asm volatile("s_waitcnt lgkmcnt(0)" ::: "memory"); __builtin_amdgcn_s_barrier(); asm volatile("" ::: "memory");
;         const int tid = wid * 64 + lane;
;         if (tid < 256) {
;             const f32x4 pp = *(const LAS f32x4*)(P + tid * 4);
;             __hip_atomic_store(xbuf + ((size_t)u.pm * 256 + tid) * 4 + u.pn, (pp[0] + pp[1]) + (pp[2] + pp[3]), __ATOMIC_RELAXED, __HIP_MEMORY_SCOPE_AGENT);
;         }
;         asm volatile("s_waitcnt vmcnt(0)" ::: "memory");
;         if (wid < 4 && lane == 0) __hip_atomic_fetch_add(cnt, 1u, __ATOMIC_RELAXED, __HIP_MEMORY_SCOPE_AGENT);
;         if (wid == 0) {
;             unsigned sp = 0;
;             while ((unsigned)__builtin_amdgcn_readfirstlane(__hip_atomic_load(cnt, __ATOMIC_RELAXED, __HIP_MEMORY_SCOPE_AGENT)) < 16u) { __builtin_amdgcn_s_sleep(2); if (++sp > (1u << 22)) break; }
;             __builtin_amdgcn_fence(__ATOMIC_ACQUIRE, "agent");
;         }
	v_permlane16_swap_b32_e32 v146, v147
	v_add_f32_e32 v146, v146, v147
	v_mov_b32_e32 v147, v146
	s_nop 1
	v_permlane32_swap_b32_e32 v146, v147
	s_and_saveexec_b64 s[8:9], s[4:5]
	v_add_f32_e32 v146, v146, v147
	ds_write_b32 v212, v146 offset:2048
	s_or_b64 exec, exec, s[8:9]
	v_mul_f32_e32 v146, v47, v47
	v_mul_f32_e32 v147, v49, v49
	v_fmac_f32_e32 v146, v46, v46
	v_fmac_f32_e32 v147, v48, v48
	v_add_f32_e32 v146, v146, v147
	v_mul_f32_e32 v147, v43, v43
	v_mul_f32_e32 v148, v45, v45
	v_fmac_f32_e32 v147, v42, v42
	v_fmac_f32_e32 v148, v44, v44
	v_add_f32_e32 v147, v147, v148
	v_add_f32_e32 v146, v146, v147
	v_mul_f32_e32 v147, v39, v39
	v_mul_f32_e32 v148, v41, v41
	v_fmac_f32_e32 v147, v38, v38
	v_fmac_f32_e32 v148, v40, v40
	v_add_f32_e32 v147, v147, v148
	v_add_f32_e32 v146, v146, v147
	v_mul_f32_e32 v147, v35, v35
	v_mul_f32_e32 v148, v37, v37
	v_fmac_f32_e32 v147, v34, v34
	v_fmac_f32_e32 v148, v36, v36
	v_add_f32_e32 v147, v147, v148
	v_add_f32_e32 v146, v146, v147
	v_mov_b32_e32 v147, v146
	s_nop 1
	v_permlane16_swap_b32_e32 v146, v147
	v_add_f32_e32 v146, v146, v147
	v_mov_b32_e32 v147, v146
	s_nop 1
	v_permlane32_swap_b32_e32 v146, v147
	s_and_saveexec_b64 s[8:9], s[4:5]
	v_add_f32_e32 v146, v146, v147
	ds_write_b32 v212, v146 offset:2304
	s_or_b64 exec, exec, s[8:9]
	v_mul_f32_e32 v146, v31, v31
	v_mul_f32_e32 v147, v33, v33
	v_fmac_f32_e32 v146, v30, v30
	v_fmac_f32_e32 v147, v32, v32
	v_add_f32_e32 v146, v146, v147
	v_mul_f32_e32 v147, v27, v27
	v_mul_f32_e32 v148, v29, v29
	v_fmac_f32_e32 v147, v26, v26
	v_fmac_f32_e32 v148, v28, v28
	v_add_f32_e32 v147, v147, v148
	v_add_f32_e32 v146, v146, v147
	v_mul_f32_e32 v147, v23, v23
	v_mul_f32_e32 v148, v25, v25
	v_fmac_f32_e32 v147, v22, v22
	v_fmac_f32_e32 v148, v24, v24
	v_add_f32_e32 v147, v147, v148
	v_add_f32_e32 v146, v146, v147
	v_mul_f32_e32 v147, v19, v19
	v_mul_f32_e32 v148, v21, v21
	v_fmac_f32_e32 v147, v18, v18
	v_fmac_f32_e32 v148, v20, v20
	v_add_f32_e32 v147, v147, v148
	v_add_f32_e32 v146, v146, v147
	v_mov_b32_e32 v147, v146
	s_nop 1
	v_permlane16_swap_b32_e32 v146, v147
	v_add_f32_e32 v146, v146, v147
	v_mov_b32_e32 v147, v146
	s_nop 1
	v_permlane32_swap_b32_e32 v146, v147
	s_and_saveexec_b64 s[8:9], s[4:5]
	v_add_f32_e32 v146, v146, v147
	ds_write_b32 v212, v146 offset:2560
	s_or_b64 exec, exec, s[8:9]
	v_mul_f32_e32 v146, v15, v15
	v_mul_f32_e32 v147, v17, v17
	v_fmac_f32_e32 v146, v14, v14
	v_fmac_f32_e32 v147, v16, v16
	v_add_f32_e32 v146, v146, v147
	v_mul_f32_e32 v147, v11, v11
	v_mul_f32_e32 v148, v13, v13
	v_fmac_f32_e32 v147, v10, v10
	v_fmac_f32_e32 v148, v12, v12
	v_add_f32_e32 v147, v147, v148
	v_add_f32_e32 v146, v146, v147
	v_mul_f32_e32 v147, v7, v7
	v_mul_f32_e32 v148, v9, v9
	v_fmac_f32_e32 v147, v6, v6
	v_fmac_f32_e32 v148, v8, v8
	v_add_f32_e32 v147, v147, v148
	v_add_f32_e32 v146, v146, v147
	v_mul_f32_e32 v147, v3, v3
	v_mul_f32_e32 v148, v5, v5
	v_fmac_f32_e32 v147, v2, v2
	v_fmac_f32_e32 v148, v4, v4
	v_add_f32_e32 v147, v147, v148
	v_add_f32_e32 v146, v146, v147
	v_mov_b32_e32 v147, v146
	s_nop 1
	v_permlane16_swap_b32_e32 v146, v147
	v_add_f32_e32 v146, v146, v147
	v_mov_b32_e32 v147, v146
	s_nop 1
	v_permlane32_swap_b32_e32 v146, v147
	s_and_saveexec_b64 s[8:9], s[4:5]
	v_add_f32_e32 v146, v146, v147
	ds_write_b32 v212, v146 offset:2816
	s_or_b64 exec, exec, s[8:9]
	s_waitcnt lgkmcnt(0)
	s_barrier
	s_ashr_i32 s29, s28, 31
	v_add_u32_e32 v215, 0x20000, v213
	s_and_saveexec_b64 s[8:9], s[6:7]
	s_cbranch_execz .LBB0_1419
	ds_read_b128 v[146:149], v215
	s_lshl_b64 s[10:11], s[28:29], 12
	v_lshl_add_u64 v[150:151], v[138:139], 0, s[10:11]
	s_mov_b32 s100, s57
	v_lshl_add_u64 v[250:251], v[150:151], 0, s[10:11]
	v_mov_b32_e32 v249, 0x800000
	v_lshl_add_u32 v248, v222, 4, v249
	v_mov_b32_e32 v249, 0
	v_lshl_add_u64 v[250:251], v[248:249], 0, v[250:251]
	s_ashr_i32 s27, s26, 31
	v_lshl_add_u64 v[150:151], s[26:27], 2, v[150:151]
	v_lshl_add_u64 v[248:249], s[26:27], 3, v[250:251]
	s_waitcnt lgkmcnt(0)
	v_mov_b32_e32 v152, v147
	v_mov_b32_e32 v153, v148
	v_mov_b32_e32 v147, v149
	v_pk_add_f32 v[146:147], v[152:153], v[146:147]
	s_nop 0
	v_pk_add_f32 v[146:147], v[146:147], v[146:147] op_sel:[0,1] op_sel_hi:[1,0]
	v_xor_b32_e32 v147, s100, v146
	global_store_dwordx2 v[248:249], v[146:147], off sc1
.LBB0_1419:
	s_or_b64 exec, exec, s[8:9]
	s_lshl_b64 s[40:41], s[28:29], 6
	s_add_u32 s10, s57, s40
	s_addc_u32 s11, s58, s41
	s_and_saveexec_b64 s[8:9], s[18:19]
	s_cbranch_execz .LBB0_1422
	s_mov_b64 s[42:43], exec
	v_mbcnt_lo_u32_b32 v146, s42, 0
	v_mbcnt_hi_u32_b32 v146, s43, v146
	v_cmp_eq_u32_e32 vcc, 0, v146
	s_and_b64 s[64:65], exec, vcc
	s_mov_b64 exec, s[64:65]
	s_cbranch_execz .LBB0_1422
	s_bcnt1_i32_b64 s27, s[42:43]
	v_mov_b32_e32 v146, s27
.LBB0_1422:
	s_or_b64 exec, exec, s[8:9]
	v_cndmask_b32_e64 v146, 0, 1, s[20:21]
	v_cmp_ne_u32_e64 s[8:9], 1, v146
	s_andn2_b64 vcc, exec, s[20:21]
	s_cbranch_vccnz .LBB0_1432
	s_branch .LBB0_1432

;     __device__ __forceinline__ void exchange(int e, float (&sv)[2][4], float (&rv)[2][4], const Unit& u, int wr, int wc, int fr, int fq, LAS unsigned char* lds, int wid, int lane) const {
;     ...
;         asm volatile("s_waitcnt vmcnt(0) lgkmcnt(0)" ::: "memory"); __builtin_amdgcn_s_barrier(); asm volatile("" ::: "memory");
;         if (tid < 256) {
;             const float* sl = xbuf + ((size_t)u.pm * 256 + tid) * 4;
;             const float t0 = __hip_atomic_load(sl + 0, __ATOMIC_RELAXED, __HIP_MEMORY_SCOPE_AGENT), t1 = __hip_atomic_load(sl + 1, __ATOMIC_RELAXED, __HIP_MEMORY_SCOPE_AGENT);
;             const float t2 = __hip_atomic_load(sl + 2, __ATOMIC_RELAXED, __HIP_MEMORY_SCOPE_AGENT), t3 = __hip_atomic_load(sl + 3, __ATOMIC_RELAXED, __HIP_MEMORY_SCOPE_AGENT);
;             Sx[tid] = 1.0f / sqrtf(((t0 + t1) + (t2 + t3)) * (1.0f / 1024.0f) + RMS_EPS);
;         }
;         asm volatile("s_waitcnt vmcnt(0) lgkmcnt(0)" ::: "memory"); __builtin_amdgcn_s_barrier(); asm volatile("" ::: "memory");
; #pragma unroll
;         for (int ai = 0; ai < 2; ++ai)
; #pragma unroll
;             for (int m = 0; m < 4; ++m) rv[ai][m] = Sx[ai * HALF + wr * 64 + m * 16 + fr];
;     }
;     __device__ __forceinline__ void fused(f32x4 (&acc)[2][2][4][2], const Unit& u, int wr, int wc, int fr, int fq, LAS unsigned char* lds, int wid, int lane) const {
;         bf16_t* hb = (bf16_t*)(ws + WS_HB);
;         const int row0 = u.pm * BM + wr * 64 + fr, col0 = u.pn * BM + wc * 32 + 8 * fq;
;         float sv[2][4], rv[2][4];
; #pragma unroll
;         for (int ai = 0; ai < 2; ++ai)
; #pragma unroll
;             for (int m = 0; m < 4; ++m) {
;                 float q = 0.f;
; #pragma unroll
;                 for (int bj = 0; bj < 2; ++bj)
; #pragma unroll
;                     for (int n = 0; n < 2; ++n) { const f32x4 x = acc[ai][bj][m][n]; q += (x[0] * x[0] + x[1] * x[1]) + (x[2] * x[2] + x[3] * x[3]); }
;                 sv[ai][m] = q;
;             }
;         exchange(0, sv, rv, u, wr, wc, fr, fq, lds, wid, lane);
;         float dep = 0.f;
; #pragma unroll
;         for (int ai = 0; ai < 2; ++ai)
; #pragma unroll
;             for (int m = 0; m < 4; ++m) {
;                 const bf16_t* hrow = hb + (size_t)(row0 + ai * HALF + m * 16) * DM + col0;
;                 asm volatile("" : "+v"(hrow) : "v"(dep));
;                 const float r1 = rv[ai][m];
.LBB0_1432:
	s_waitcnt lgkmcnt(0)
	s_barrier
	s_and_saveexec_b64 s[42:43], s[6:7]
	s_cbranch_execz .LBB0_1434
	s_lshl_b64 s[10:11], s[28:29], 12
	v_lshl_add_u64 v[146:147], v[138:139], 0, s[10:11]
	v_lshl_or_b32 v232, s26, 8, v222
	v_lshlrev_b32_e32 v232, 2, v232
	global_load_dword v233, v232, s[14:15]
	v_lshl_add_u64 v[250:251], v[146:147], 0, s[10:11]
	v_mov_b32_e32 v249, 0x800000
	v_lshl_add_u32 v248, v222, 4, v249
	v_mov_b32_e32 v249, 0
	v_lshl_add_u64 v[250:251], v[248:249], 0, v[250:251]
	s_mov_b32 s101, 0x4000
.Lx_poll4:
	global_load_dwordx4 v[236:239], v[250:251], off sc1
	global_load_dwordx4 v[240:243], v[250:251], off offset:16 sc1
	s_waitcnt vmcnt(0)
	v_xor_b32_e32 v244, v236, v237
	v_xor_b32_e32 v245, v238, v239
	v_xor_b32_e32 v246, v240, v241
	v_xor_b32_e32 v247, v242, v243
	v_xor_b32_e32 v244, s100, v244
	v_xor_b32_e32 v245, s100, v245
	v_xor_b32_e32 v246, s100, v246
	v_xor_b32_e32 v247, s100, v247
	v_or3_b32 v244, v244, v245, v246
	v_or_b32_e32 v244, v244, v247
	v_cmp_eq_u32_e32 vcc, 0, v244
	s_nop 1
	s_cmp_eq_u64 vcc, exec
	s_cbranch_scc1 .Lx_rdy4
	s_sleep 1
	s_add_i32 s101, s101, -1
	s_cmp_lg_u32 s101, 0
	s_cbranch_scc1 .Lx_poll4
.Lx_rdy4:
	s_mov_b32 s10, 0xf800000
	v_mov_b32_e32 v148, v236
	v_mov_b32_e32 v150, v238
	v_mov_b32_e32 v149, v240
	v_mov_b32_e32 v151, v242
	v_pk_add_f32 v[146:147], v[148:149], v[150:151]
	s_nop 0
	v_add_f32_e32 v146, v146, v147
	v_fmamk_f32 v146, v146, 0x3a800000, v228
	v_mul_f32_e32 v147, 0x4f800000, v146
	v_cmp_gt_f32_e32 vcc, s10, v146
	s_nop 1
	v_cndmask_b32_e32 v146, v146, v147, vcc
	v_sqrt_f32_e32 v147, v146
	s_nop 0
	v_add_u32_e32 v148, -1, v147
	v_add_u32_e32 v149, 1, v147
	v_fma_f32 v150, -v148, v147, v146
	v_fma_f32 v151, -v149, v147, v146
	v_cmp_ge_f32_e64 s[10:11], 0, v150
	s_nop 1
	v_cndmask_b32_e64 v147, v147, v148, s[10:11]
	v_cmp_lt_f32_e64 s[10:11], 0, v151
	s_nop 1
	v_cndmask_b32_e64 v147, v147, v149, s[10:11]
	v_mul_f32_e32 v148, 0x37800000, v147
	v_cndmask_b32_e32 v147, v147, v148, vcc
	v_cmp_class_f32_e32 vcc, v146, v227
	s_nop 1
	v_cndmask_b32_e32 v146, v147, v146, vcc
	v_div_scale_f32 v147, s[10:11], v146, v146, 1.0
	v_rcp_f32_e32 v148, v147
	v_div_scale_f32 v149, vcc, 1.0, v146, 1.0
	v_fma_f32 v150, -v147, v148, 1.0
	v_fmac_f32_e32 v148, v150, v148
	v_mul_f32_e32 v150, v149, v148
	v_fma_f32 v151, -v147, v150, v149
	v_fmac_f32_e32 v150, v151, v148
	v_fma_f32 v147, -v147, v150, v149
	v_div_fmas_f32 v147, v147, v148, v150
	v_div_fixup_f32 v146, v147, v146, 1.0
	ds_write_b32 v209, v146
	v_mov_b32_e32 v234, 0x21400
	v_lshl_add_u32 v232, v222, 2, v234
	ds_write_b32 v232, v233
.LBB0_1434:
	s_or_b64 exec, exec, s[42:43]
	v_mov_b32_e32 v234, 0x21400
	v_lshl_add_u32 v231, v208, 2, v234
	v_lshl_add_u32 v146, s28, 8, v1
	v_lshl_or_b32 v156, s26, 8, v208
	v_ashrrev_i32_e32 v157, 31, v156
	v_ashrrev_i32_e32 v147, 31, v146
	v_lshl_add_u64 v[158:159], v[156:157], 1, s[22:23]
	v_lshlrev_b64 v[148:149], 11, v[146:147]
	v_lshl_add_u64 v[148:149], v[158:159], 0, v[148:149]
	s_waitcnt vmcnt(0) lgkmcnt(0)
	s_barrier
	v_mov_b64_e32 v[166:167], v[148:149]
	ds_read2_b32 v[160:161], v214 offset1:16
	ds_read2_b32 v[170:171], v214 offset0:32 offset1:48
	ds_read2_b32 v[168:169], v214 offset0:128 offset1:144
	ds_read2_b32 v[154:155], v214 offset0:160 offset1:176
	v_mov_b64_e32 v[234:235], v[148:149]
	s_mov_b32 s101, 0
	global_load_dwordx4 v[236:239], v[234:235], off
	global_load_dwordx4 v[240:243], v[234:235], off offset:256
	s_mov_b32 s100, 0x8000
	v_lshl_add_u64 v[232:233], v[234:235], 0, s[100:101]
	global_load_dwordx4 v[244:247], v[232:233], off
	global_load_dwordx4 v[248:251], v[232:233], off offset:256
	v_lshl_add_u64 v[156:157], v[156:157], 2, s[14:15]
	s_waitcnt lgkmcnt(0)
	v_pk_mul_f32 v[128:129], v[128:129], v[160:161] op_sel_hi:[1,0]
	v_pk_mul_f32 v[182:183], v[126:127], v[160:161] op_sel_hi:[1,0]
	v_pk_mul_f32 v[124:125], v[124:125], v[160:161] op_sel_hi:[1,0]
	v_pk_mul_f32 v[120:121], v[120:121], v[160:161] op_sel_hi:[1,0]
	v_pk_mul_f32 v[116:117], v[116:117], v[160:161] op_sel_hi:[1,0]
	v_mov_b32_e32 v186, v161
	v_pk_mul_f32 v[112:113], v[112:113], v[186:187] op_sel_hi:[1,0]
	v_pk_mul_f32 v[108:109], v[108:109], v[186:187] op_sel_hi:[1,0]
	v_pk_mul_f32 v[104:105], v[104:105], v[186:187] op_sel_hi:[1,0]
	v_pk_mul_f32 v[100:101], v[100:101], v[186:187] op_sel_hi:[1,0]
	v_pk_mul_f32 v[96:97], v[96:97], v[170:171] op_sel_hi:[1,0]
	v_pk_mul_f32 v[188:189], v[94:95], v[170:171] op_sel_hi:[1,0]
	v_pk_mul_f32 v[92:93], v[92:93], v[170:171] op_sel_hi:[1,0]
	v_pk_mul_f32 v[88:89], v[88:89], v[170:171] op_sel_hi:[1,0]
	v_pk_mul_f32 v[84:85], v[84:85], v[170:171] op_sel_hi:[1,0]
	v_mov_b32_e32 v192, v171
	v_pk_mul_f32 v[80:81], v[80:81], v[192:193] op_sel_hi:[1,0]
	v_pk_mul_f32 v[76:77], v[76:77], v[192:193] op_sel_hi:[1,0]
	v_pk_mul_f32 v[72:73], v[72:73], v[192:193] op_sel_hi:[1,0]
	v_pk_mul_f32 v[68:69], v[68:69], v[192:193] op_sel_hi:[1,0]
	v_pk_mul_f32 v[64:65], v[64:65], v[168:169] op_sel_hi:[1,0]
	v_pk_mul_f32 v[194:195], v[62:63], v[168:169] op_sel_hi:[1,0]
	v_pk_mul_f32 v[60:61], v[60:61], v[168:169] op_sel_hi:[1,0]
	v_pk_mul_f32 v[56:57], v[56:57], v[168:169] op_sel_hi:[1,0]
	v_pk_mul_f32 v[52:53], v[52:53], v[168:169] op_sel_hi:[1,0]
	v_mov_b32_e32 v198, v169
	v_pk_mul_f32 v[48:49], v[48:49], v[198:199] op_sel_hi:[1,0]
	v_pk_mul_f32 v[44:45], v[44:45], v[198:199] op_sel_hi:[1,0]
	v_pk_mul_f32 v[38:39], v[38:39], v[198:199] op_sel_hi:[1,0]
	v_pk_mul_f32 v[40:41], v[40:41], v[198:199] op_sel_hi:[1,0]
	v_pk_mul_f32 v[36:37], v[36:37], v[198:199] op_sel_hi:[1,0]
	v_pk_mul_f32 v[34:35], v[34:35], v[198:199] op_sel_hi:[1,0]
	v_pk_mul_f32 v[32:33], v[32:33], v[154:155] op_sel_hi:[1,0]
	v_pk_mul_f32 v[28:29], v[28:29], v[154:155] op_sel_hi:[1,0]
	v_pk_mul_f32 v[26:27], v[26:27], v[154:155] op_sel_hi:[1,0]
	v_pk_mul_f32 v[30:31], v[30:31], v[154:155] op_sel_hi:[1,0]
	v_pk_mul_f32 v[22:23], v[22:23], v[154:155] op_sel_hi:[1,0]
	v_pk_mul_f32 v[24:25], v[24:25], v[154:155] op_sel_hi:[1,0]
	v_pk_mul_f32 v[20:21], v[20:21], v[154:155] op_sel_hi:[1,0]
	v_pk_mul_f32 v[18:19], v[18:19], v[154:155] op_sel_hi:[1,0]
	v_add_u32_e32 v206, 0xb0, v146
	v_ashrrev_i32_e32 v207, 31, v206
	s_waitcnt vmcnt(2)
;     __device__ __forceinline__ void fused(f32x4 (&acc)[2][2][4][2], const Unit& u, int wr, int wc, int fr, int fq, LAS unsigned char* lds, int wid, int lane) const {
;     ...
;                 const bf16_t* hrow = hb + (size_t)(row0 + ai * HALF + m * 16) * DM + col0;
;                 asm volatile("" : "+v"(hrow) : "v"(dep));
;                 const float r1 = rv[ai][m];
;                 float q = 0.f;
; #pragma unroll
;                 for (int bj = 0; bj < 2; ++bj) {
;                     const u32x4 hv = *(const u32x4*)(hrow + bj * HALF);
;                     const f32x4 h0 = (f32x4){__uint_as_float(hv.x << 16), __uint_as_float(hv.x & 0xffff0000u), __uint_as_float(hv.y << 16), __uint_as_float(hv.y & 0xffff0000u)};
;                     const f32x4 h1 = (f32x4){__uint_as_float(hv.z << 16), __uint_as_float(hv.z & 0xffff0000u), __uint_as_float(hv.w << 16), __uint_as_float(hv.w & 0xffff0000u)};
;                     const f32x4 gg0 = *(const f32x4*)(gpost + col0 + bj * HALF), gg1 = *(const f32x4*)(gpost + col0 + bj * HALF + 4);
;                     f32x4 x0 = h0 + acc[ai][bj][m][0] * r1 * gg0, x1 = h1 + acc[ai][bj][m][1] * r1 * gg1;
;                     acc[ai][bj][m][0] = x0; acc[ai][bj][m][1] = x1;
;                     q += ((x0[0] * x0[0] + x0[1] * x0[1]) + (x0[2] * x0[2] + x0[3] * x0[3])) + ((x1[0] * x1[0] + x1[1] * x1[1]) + (x1[2] * x1[2] + x1[3] * x1[3]));
;                 }
;                 sv[ai][m] = q;
;                 dep = q;
	ds_read_b128 v[150:153], v231 offset:16
	ds_read_b128 v[162:165], v231 offset:0
	v_lshlrev_b32_e32 v172, 16, v236
	v_and_b32_e32 v173, 0xffff0000, v236
	v_lshlrev_b32_e32 v174, 16, v237
	v_and_b32_e32 v175, 0xffff0000, v237
	v_lshlrev_b32_e32 v176, 16, v238
	v_and_b32_e32 v177, 0xffff0000, v238
	v_lshlrev_b32_e32 v178, 16, v239
	v_and_b32_e32 v179, 0xffff0000, v239
	s_mov_b32 s100, 0x10000
	v_lshl_add_u64 v[232:233], v[234:235], 0, s[100:101]
	global_load_dwordx4 v[236:239], v[232:233], off
	s_waitcnt lgkmcnt(0)
	v_pk_fma_f32 v[126:127], v[128:129], v[164:165], v[174:175]
	v_pk_fma_f32 v[128:129], v[182:183], v[162:163], v[172:173]
	v_pk_mul_f32 v[162:163], v[122:123], v[160:161] op_sel_hi:[1,0]
	v_pk_fma_f32 v[122:123], v[124:125], v[152:153], v[178:179]
	v_pk_fma_f32 v[124:125], v[162:163], v[150:151], v[176:177]
	ds_read_b128 v[150:153], v231 offset:528
	ds_read_b128 v[162:165], v231 offset:512
	v_pk_mul_f32 v[178:179], v[118:119], v[160:161] op_sel_hi:[1,0]
	s_waitcnt lgkmcnt(0)
	v_lshlrev_b32_e32 v166, 16, v240
	v_and_b32_e32 v167, 0xffff0000, v240
	v_lshlrev_b32_e32 v172, 16, v241
	v_and_b32_e32 v173, 0xffff0000, v241
	v_lshlrev_b32_e32 v174, 16, v242
	v_and_b32_e32 v175, 0xffff0000, v242
	v_lshlrev_b32_e32 v176, 16, v243
	v_and_b32_e32 v177, 0xffff0000, v243
	global_load_dwordx4 v[240:243], v[232:233], off offset:256
	s_waitcnt lgkmcnt(0)
	v_pk_fma_f32 v[118:119], v[120:121], v[164:165], v[172:173]
	v_pk_fma_f32 v[120:121], v[178:179], v[162:163], v[166:167]
	v_pk_mul_f32 v[162:163], v[114:115], v[160:161] op_sel_hi:[1,0]
	v_pk_fma_f32 v[114:115], v[116:117], v[152:153], v[176:177]
	v_mov_b32_e32 v152, v129
	v_mov_b32_e32 v153, v121
	v_pk_fma_f32 v[116:117], v[162:163], v[150:151], v[174:175]
	v_mov_b32_e32 v150, v128
	v_mov_b32_e32 v151, v120
	v_pk_mul_f32 v[152:153], v[152:153], v[152:153]
	v_mov_b32_e32 v162, v127
	v_mov_b32_e32 v163, v119
	v_pk_fma_f32 v[150:151], v[150:151], v[150:151], v[152:153]
	v_mov_b32_e32 v152, v126
	v_mov_b32_e32 v153, v118
	v_pk_mul_f32 v[162:163], v[162:163], v[162:163]
	v_mov_b32_e32 v164, v123
	v_pk_fma_f32 v[152:153], v[152:153], v[152:153], v[162:163]
	v_mov_b32_e32 v162, v125
	v_mov_b32_e32 v163, v117
	v_pk_add_f32 v[150:151], v[150:151], v[152:153]
	v_mov_b32_e32 v152, v124
	v_mov_b32_e32 v153, v116
	v_pk_mul_f32 v[162:163], v[162:163], v[162:163]
	v_mov_b32_e32 v165, v115
	v_pk_fma_f32 v[152:153], v[152:153], v[152:153], v[162:163]
	v_mov_b32_e32 v162, v122
	v_mov_b32_e32 v163, v114
	v_pk_mul_f32 v[164:165], v[164:165], v[164:165]
	v_pk_mul_f32 v[160:161], v[110:111], v[186:187] op_sel_hi:[1,0]
	v_pk_fma_f32 v[162:163], v[162:163], v[162:163], v[164:165]
	s_nop 0
	v_pk_add_f32 v[152:153], v[152:153], v[162:163]
	s_nop 0
	v_pk_add_f32 v[150:151], v[150:151], v[152:153]
	s_nop 0
	v_add_f32_e32 v216, v150, v151
	v_or_b32_e32 v150, 16, v146
	v_ashrrev_i32_e32 v151, 31, v150
	v_lshlrev_b64 v[152:153], 11, v[150:151]
	v_lshl_add_u64 v[152:153], v[158:159], 0, v[152:153]
	v_mov_b64_e32 v[162:163], v[152:153]
	s_waitcnt vmcnt(2)
	ds_read_b128 v[164:167], v231 offset:16
	ds_read_b128 v[172:175], v231 offset:0
	v_lshlrev_b32_e32 v176, 16, v244
	v_and_b32_e32 v177, 0xffff0000, v244
	v_lshlrev_b32_e32 v178, 16, v245
	v_and_b32_e32 v179, 0xffff0000, v245
	v_lshlrev_b32_e32 v182, 16, v246
	v_and_b32_e32 v183, 0xffff0000, v246
	v_lshlrev_b32_e32 v184, 16, v247
	v_and_b32_e32 v185, 0xffff0000, v247
	s_mov_b32 s100, 0x18000
	v_lshl_add_u64 v[232:233], v[234:235], 0, s[100:101]
	global_load_dwordx4 v[244:247], v[232:233], off
	s_waitcnt lgkmcnt(0)
	v_pk_fma_f32 v[110:111], v[112:113], v[174:175], v[178:179]
	v_pk_fma_f32 v[112:113], v[160:161], v[172:173], v[176:177]
	v_pk_mul_f32 v[160:161], v[106:107], v[186:187] op_sel_hi:[1,0]
	v_pk_fma_f32 v[106:107], v[108:109], v[166:167], v[184:185]
	v_pk_fma_f32 v[108:109], v[160:161], v[164:165], v[182:183]
	ds_read_b128 v[160:163], v231 offset:528
	ds_read_b128 v[164:167], v231 offset:512
	v_pk_mul_f32 v[182:183], v[102:103], v[186:187] op_sel_hi:[1,0]
	s_waitcnt lgkmcnt(0)
	v_lshlrev_b32_e32 v172, 16, v248
	v_and_b32_e32 v173, 0xffff0000, v248
	v_lshlrev_b32_e32 v174, 16, v249
	v_and_b32_e32 v175, 0xffff0000, v249
	v_lshlrev_b32_e32 v176, 16, v250
	v_and_b32_e32 v177, 0xffff0000, v250
	v_lshlrev_b32_e32 v178, 16, v251
	v_and_b32_e32 v179, 0xffff0000, v251
	global_load_dwordx4 v[248:251], v[232:233], off offset:256
	s_waitcnt lgkmcnt(0)
	v_pk_fma_f32 v[102:103], v[104:105], v[166:167], v[174:175]
	v_pk_fma_f32 v[104:105], v[182:183], v[164:165], v[172:173]
	v_pk_mul_f32 v[164:165], v[98:99], v[186:187] op_sel_hi:[1,0]
	v_pk_fma_f32 v[98:99], v[100:101], v[162:163], v[178:179]
	v_mov_b32_e32 v162, v113
	v_mov_b32_e32 v163, v105
	v_pk_fma_f32 v[100:101], v[164:165], v[160:161], v[176:177]
	v_mov_b32_e32 v160, v112
	v_mov_b32_e32 v161, v104
	v_pk_mul_f32 v[162:163], v[162:163], v[162:163]
	v_mov_b32_e32 v164, v111
	v_mov_b32_e32 v165, v103
	v_pk_fma_f32 v[160:161], v[160:161], v[160:161], v[162:163]
	v_mov_b32_e32 v162, v110
	v_mov_b32_e32 v163, v102
	v_pk_mul_f32 v[164:165], v[164:165], v[164:165]
	v_mov_b32_e32 v166, v107
	v_pk_fma_f32 v[162:163], v[162:163], v[162:163], v[164:165]
	v_mov_b32_e32 v164, v109
	v_mov_b32_e32 v165, v101
	v_pk_add_f32 v[160:161], v[160:161], v[162:163]
	v_mov_b32_e32 v162, v108
	v_mov_b32_e32 v163, v100
	v_pk_mul_f32 v[164:165], v[164:165], v[164:165]
	v_mov_b32_e32 v167, v99
	v_pk_fma_f32 v[162:163], v[162:163], v[162:163], v[164:165]
	v_mov_b32_e32 v164, v106
	v_mov_b32_e32 v165, v98
	v_pk_mul_f32 v[166:167], v[166:167], v[166:167]
	s_nop 0
	v_pk_fma_f32 v[164:165], v[164:165], v[164:165], v[166:167]
	s_nop 0
	v_pk_add_f32 v[162:163], v[162:163], v[164:165]
	s_nop 0
	v_pk_add_f32 v[160:161], v[160:161], v[162:163]
	s_nop 0
	v_add_f32_e32 v217, v160, v161
	v_or_b32_e32 v160, 32, v146
	v_ashrrev_i32_e32 v161, 31, v160
	v_lshlrev_b64 v[162:163], 11, v[160:161]
	v_lshl_add_u64 v[162:163], v[158:159], 0, v[162:163]
	v_mov_b64_e32 v[164:165], v[162:163]
	s_waitcnt vmcnt(2)
;     __device__ __forceinline__ void fused(f32x4 (&acc)[2][2][4][2], const Unit& u, int wr, int wc, int fr, int fq, LAS unsigned char* lds, int wid, int lane) const {
;     ...
;                 const bf16_t* hrow = hb + (size_t)(row0 + ai * HALF + m * 16) * DM + col0;
;                 asm volatile("" : "+v"(hrow) : "v"(dep));
;                 const float r1 = rv[ai][m];
;                 float q = 0.f;
; #pragma unroll
;                 for (int bj = 0; bj < 2; ++bj) {
;                     const u32x4 hv = *(const u32x4*)(hrow + bj * HALF);
;                     const f32x4 h0 = (f32x4){__uint_as_float(hv.x << 16), __uint_as_float(hv.x & 0xffff0000u), __uint_as_float(hv.y << 16), __uint_as_float(hv.y & 0xffff0000u)};
;                     const f32x4 h1 = (f32x4){__uint_as_float(hv.z << 16), __uint_as_float(hv.z & 0xffff0000u), __uint_as_float(hv.w << 16), __uint_as_float(hv.w & 0xffff0000u)};
;                     const f32x4 gg0 = *(const f32x4*)(gpost + col0 + bj * HALF), gg1 = *(const f32x4*)(gpost + col0 + bj * HALF + 4);
;                     f32x4 x0 = h0 + acc[ai][bj][m][0] * r1 * gg0, x1 = h1 + acc[ai][bj][m][1] * r1 * gg1;
;                     acc[ai][bj][m][0] = x0; acc[ai][bj][m][1] = x1;
;                     q += ((x0[0] * x0[0] + x0[1] * x0[1]) + (x0[2] * x0[2] + x0[3] * x0[3])) + ((x1[0] * x1[0] + x1[1] * x1[1]) + (x1[2] * x1[2] + x1[3] * x1[3]));
;                 }
;                 sv[ai][m] = q;
;                 dep = q;
	ds_read_b128 v[172:175], v231 offset:16
	ds_read_b128 v[176:179], v231 offset:0
	v_lshlrev_b32_e32 v166, 16, v236
	v_and_b32_e32 v167, 0xffff0000, v236
	v_lshlrev_b32_e32 v182, 16, v237
	v_and_b32_e32 v183, 0xffff0000, v237
	v_lshlrev_b32_e32 v184, 16, v238
	v_and_b32_e32 v185, 0xffff0000, v238
	v_lshlrev_b32_e32 v186, 16, v239
	v_and_b32_e32 v187, 0xffff0000, v239
	s_mov_b32 s100, 0x40000
	v_lshl_add_u64 v[232:233], v[234:235], 0, s[100:101]
	global_load_dwordx4 v[236:239], v[232:233], off
	s_waitcnt lgkmcnt(0)
	v_pk_fma_f32 v[94:95], v[96:97], v[178:179], v[182:183]
	v_pk_fma_f32 v[96:97], v[188:189], v[176:177], v[166:167]
	v_pk_mul_f32 v[166:167], v[90:91], v[170:171] op_sel_hi:[1,0]
	v_pk_fma_f32 v[90:91], v[92:93], v[174:175], v[186:187]
	v_pk_fma_f32 v[92:93], v[166:167], v[172:173], v[184:185]
	ds_read_b128 v[164:167], v231 offset:528
	ds_read_b128 v[172:175], v231 offset:512
	v_pk_mul_f32 v[186:187], v[86:87], v[170:171] op_sel_hi:[1,0]
	s_waitcnt lgkmcnt(0)
	v_lshlrev_b32_e32 v176, 16, v240
	v_and_b32_e32 v177, 0xffff0000, v240
	v_lshlrev_b32_e32 v178, 16, v241
	v_and_b32_e32 v179, 0xffff0000, v241
	v_lshlrev_b32_e32 v182, 16, v242
	v_and_b32_e32 v183, 0xffff0000, v242
	v_lshlrev_b32_e32 v184, 16, v243
	v_and_b32_e32 v185, 0xffff0000, v243
	global_load_dwordx4 v[240:243], v[232:233], off offset:256
	s_waitcnt lgkmcnt(0)
	v_pk_fma_f32 v[86:87], v[88:89], v[174:175], v[178:179]
	v_pk_fma_f32 v[88:89], v[186:187], v[172:173], v[176:177]
	v_pk_mul_f32 v[172:173], v[82:83], v[170:171] op_sel_hi:[1,0]
	v_pk_fma_f32 v[82:83], v[84:85], v[166:167], v[184:185]
	v_mov_b32_e32 v166, v97
	v_mov_b32_e32 v167, v89
	v_pk_fma_f32 v[84:85], v[172:173], v[164:165], v[182:183]
	v_mov_b32_e32 v164, v96
	v_mov_b32_e32 v165, v88
	v_pk_mul_f32 v[166:167], v[166:167], v[166:167]
	v_mov_b32_e32 v172, v95
	v_mov_b32_e32 v173, v87
	v_pk_fma_f32 v[164:165], v[164:165], v[164:165], v[166:167]
	v_mov_b32_e32 v166, v94
	v_mov_b32_e32 v167, v86
	v_pk_mul_f32 v[172:173], v[172:173], v[172:173]
	v_mov_b32_e32 v174, v91
	v_pk_fma_f32 v[166:167], v[166:167], v[166:167], v[172:173]
	v_mov_b32_e32 v172, v93
	v_mov_b32_e32 v173, v85
	v_pk_add_f32 v[164:165], v[164:165], v[166:167]
	v_mov_b32_e32 v166, v92
	v_mov_b32_e32 v167, v84
	v_pk_mul_f32 v[172:173], v[172:173], v[172:173]
	v_mov_b32_e32 v175, v83
	v_pk_fma_f32 v[166:167], v[166:167], v[166:167], v[172:173]
	v_mov_b32_e32 v172, v90
	v_mov_b32_e32 v173, v82
	v_pk_mul_f32 v[174:175], v[174:175], v[174:175]
	v_pk_mul_f32 v[170:171], v[78:79], v[192:193] op_sel_hi:[1,0]
	v_pk_fma_f32 v[172:173], v[172:173], v[172:173], v[174:175]
	s_nop 0
	v_pk_add_f32 v[166:167], v[166:167], v[172:173]
	s_nop 0
	v_pk_add_f32 v[164:165], v[164:165], v[166:167]
	s_nop 0
	v_add_f32_e32 v218, v164, v165
	v_or_b32_e32 v164, 48, v146
	v_ashrrev_i32_e32 v165, 31, v164
	v_lshlrev_b64 v[166:167], 11, v[164:165]
	v_lshl_add_u64 v[166:167], v[158:159], 0, v[166:167]
	v_mov_b64_e32 v[172:173], v[166:167]
	s_waitcnt vmcnt(2)
	ds_read_b128 v[174:177], v231 offset:16
	ds_read_b128 v[182:185], v231 offset:0
	v_lshlrev_b32_e32 v178, 16, v244
	v_and_b32_e32 v179, 0xffff0000, v244
	v_lshlrev_b32_e32 v186, 16, v245
	v_and_b32_e32 v187, 0xffff0000, v245
	v_lshlrev_b32_e32 v188, 16, v246
	v_and_b32_e32 v189, 0xffff0000, v246
	v_lshlrev_b32_e32 v190, 16, v247
	v_and_b32_e32 v191, 0xffff0000, v247
	s_mov_b32 s100, 0x48000
	v_lshl_add_u64 v[232:233], v[234:235], 0, s[100:101]
	global_load_dwordx4 v[244:247], v[232:233], off
	s_waitcnt lgkmcnt(0)
	v_pk_fma_f32 v[78:79], v[80:81], v[184:185], v[186:187]
	v_pk_fma_f32 v[80:81], v[170:171], v[182:183], v[178:179]
	v_pk_mul_f32 v[170:171], v[74:75], v[192:193] op_sel_hi:[1,0]
	v_pk_fma_f32 v[74:75], v[76:77], v[176:177], v[190:191]
	v_pk_fma_f32 v[76:77], v[170:171], v[174:175], v[188:189]
	ds_read_b128 v[170:173], v231 offset:528
	ds_read_b128 v[174:177], v231 offset:512
	v_pk_mul_f32 v[188:189], v[70:71], v[192:193] op_sel_hi:[1,0]
	s_waitcnt lgkmcnt(0)
	v_lshlrev_b32_e32 v178, 16, v248
	v_and_b32_e32 v179, 0xffff0000, v248
	v_lshlrev_b32_e32 v182, 16, v249
	v_and_b32_e32 v183, 0xffff0000, v249
	v_lshlrev_b32_e32 v184, 16, v250
	v_and_b32_e32 v185, 0xffff0000, v250
	v_lshlrev_b32_e32 v186, 16, v251
	v_and_b32_e32 v187, 0xffff0000, v251
	global_load_dwordx4 v[248:251], v[232:233], off offset:256
	s_waitcnt lgkmcnt(0)
	v_pk_fma_f32 v[70:71], v[72:73], v[176:177], v[182:183]
	v_pk_fma_f32 v[72:73], v[188:189], v[174:175], v[178:179]
	v_pk_mul_f32 v[174:175], v[66:67], v[192:193] op_sel_hi:[1,0]
	v_pk_fma_f32 v[66:67], v[68:69], v[172:173], v[186:187]
	v_mov_b32_e32 v172, v81
	v_mov_b32_e32 v173, v73
	v_pk_fma_f32 v[68:69], v[174:175], v[170:171], v[184:185]
	v_mov_b32_e32 v170, v80
	v_mov_b32_e32 v171, v72
	v_pk_mul_f32 v[172:173], v[172:173], v[172:173]
	v_mov_b32_e32 v174, v79
	v_mov_b32_e32 v175, v71
	v_pk_fma_f32 v[170:171], v[170:171], v[170:171], v[172:173]
	v_mov_b32_e32 v172, v78
	v_mov_b32_e32 v173, v70
	v_pk_mul_f32 v[174:175], v[174:175], v[174:175]
	v_mov_b32_e32 v176, v75
	v_pk_fma_f32 v[172:173], v[172:173], v[172:173], v[174:175]
	v_mov_b32_e32 v174, v77
	v_mov_b32_e32 v175, v69
	v_pk_add_f32 v[170:171], v[170:171], v[172:173]
	v_mov_b32_e32 v172, v76
	v_mov_b32_e32 v173, v68
	v_pk_mul_f32 v[174:175], v[174:175], v[174:175]
	v_mov_b32_e32 v177, v67
	v_pk_fma_f32 v[172:173], v[172:173], v[172:173], v[174:175]
	v_mov_b32_e32 v174, v74
	v_mov_b32_e32 v175, v66
	v_pk_mul_f32 v[176:177], v[176:177], v[176:177]
	s_nop 0
	v_pk_fma_f32 v[174:175], v[174:175], v[174:175], v[176:177]
	s_nop 0
	v_pk_add_f32 v[172:173], v[172:173], v[174:175]
	s_nop 0
	v_pk_add_f32 v[170:171], v[170:171], v[172:173]
	s_nop 0
	v_add_f32_e32 v219, v170, v171
	v_add_u32_e32 v170, 0x80, v146
	v_ashrrev_i32_e32 v171, 31, v170
	v_lshlrev_b64 v[172:173], 11, v[170:171]
	v_lshl_add_u64 v[172:173], v[158:159], 0, v[172:173]
	v_mov_b64_e32 v[174:175], v[172:173]
	s_waitcnt vmcnt(2)
;     __device__ __forceinline__ void fused(f32x4 (&acc)[2][2][4][2], const Unit& u, int wr, int wc, int fr, int fq, LAS unsigned char* lds, int wid, int lane) const {
;     ...
;                 const bf16_t* hrow = hb + (size_t)(row0 + ai * HALF + m * 16) * DM + col0;
;                 asm volatile("" : "+v"(hrow) : "v"(dep));
;                 const float r1 = rv[ai][m];
;                 float q = 0.f;
; #pragma unroll
;                 for (int bj = 0; bj < 2; ++bj) {
;                     const u32x4 hv = *(const u32x4*)(hrow + bj * HALF);
;                     const f32x4 h0 = (f32x4){__uint_as_float(hv.x << 16), __uint_as_float(hv.x & 0xffff0000u), __uint_as_float(hv.y << 16), __uint_as_float(hv.y & 0xffff0000u)};
;                     const f32x4 h1 = (f32x4){__uint_as_float(hv.z << 16), __uint_as_float(hv.z & 0xffff0000u), __uint_as_float(hv.w << 16), __uint_as_float(hv.w & 0xffff0000u)};
;                     const f32x4 gg0 = *(const f32x4*)(gpost + col0 + bj * HALF), gg1 = *(const f32x4*)(gpost + col0 + bj * HALF + 4);
;                     f32x4 x0 = h0 + acc[ai][bj][m][0] * r1 * gg0, x1 = h1 + acc[ai][bj][m][1] * r1 * gg1;
;                     acc[ai][bj][m][0] = x0; acc[ai][bj][m][1] = x1;
;                     q += ((x0[0] * x0[0] + x0[1] * x0[1]) + (x0[2] * x0[2] + x0[3] * x0[3])) + ((x1[0] * x1[0] + x1[1] * x1[1]) + (x1[2] * x1[2] + x1[3] * x1[3]));
;                 }
;                 sv[ai][m] = q;
;                 dep = q;
	ds_read_b128 v[176:179], v231 offset:16
	ds_read_b128 v[182:185], v231 offset:0
	v_lshlrev_b32_e32 v186, 16, v236
	v_and_b32_e32 v187, 0xffff0000, v236
	v_lshlrev_b32_e32 v188, 16, v237
	v_and_b32_e32 v189, 0xffff0000, v237
	v_lshlrev_b32_e32 v190, 16, v238
	v_and_b32_e32 v191, 0xffff0000, v238
	v_lshlrev_b32_e32 v192, 16, v239
	v_and_b32_e32 v193, 0xffff0000, v239
	s_mov_b32 s100, 0x50000
	v_lshl_add_u64 v[232:233], v[234:235], 0, s[100:101]
	global_load_dwordx4 v[236:239], v[232:233], off
	s_waitcnt lgkmcnt(0)
	v_pk_fma_f32 v[62:63], v[64:65], v[184:185], v[188:189]
	v_pk_fma_f32 v[64:65], v[194:195], v[182:183], v[186:187]
	v_pk_mul_f32 v[182:183], v[58:59], v[168:169] op_sel_hi:[1,0]
	v_pk_fma_f32 v[58:59], v[60:61], v[178:179], v[192:193]
	v_pk_fma_f32 v[60:61], v[182:183], v[176:177], v[190:191]
	ds_read_b128 v[174:177], v231 offset:528
	ds_read_b128 v[182:185], v231 offset:512
	v_pk_mul_f32 v[192:193], v[54:55], v[168:169] op_sel_hi:[1,0]
	s_waitcnt lgkmcnt(0)
	v_lshlrev_b32_e32 v178, 16, v240
	v_and_b32_e32 v179, 0xffff0000, v240
	v_lshlrev_b32_e32 v186, 16, v241
	v_and_b32_e32 v187, 0xffff0000, v241
	v_lshlrev_b32_e32 v188, 16, v242
	v_and_b32_e32 v189, 0xffff0000, v242
	v_lshlrev_b32_e32 v190, 16, v243
	v_and_b32_e32 v191, 0xffff0000, v243
	global_load_dwordx4 v[240:243], v[232:233], off offset:256
	s_waitcnt lgkmcnt(0)
	v_pk_fma_f32 v[54:55], v[56:57], v[184:185], v[186:187]
	v_pk_fma_f32 v[56:57], v[192:193], v[182:183], v[178:179]
	v_pk_mul_f32 v[178:179], v[50:51], v[168:169] op_sel_hi:[1,0]
	v_pk_fma_f32 v[50:51], v[52:53], v[176:177], v[190:191]
	v_mov_b32_e32 v176, v65
	v_mov_b32_e32 v177, v57
	v_pk_fma_f32 v[52:53], v[178:179], v[174:175], v[188:189]
	v_mov_b32_e32 v174, v64
	v_mov_b32_e32 v175, v56
	v_pk_mul_f32 v[176:177], v[176:177], v[176:177]
	v_mov_b32_e32 v178, v63
	v_mov_b32_e32 v179, v55
	v_pk_fma_f32 v[174:175], v[174:175], v[174:175], v[176:177]
	v_mov_b32_e32 v176, v62
	v_mov_b32_e32 v177, v54
	v_pk_mul_f32 v[178:179], v[178:179], v[178:179]
	v_mov_b32_e32 v182, v59
	v_pk_fma_f32 v[176:177], v[176:177], v[176:177], v[178:179]
	v_mov_b32_e32 v178, v61
	v_mov_b32_e32 v179, v53
	v_pk_add_f32 v[174:175], v[174:175], v[176:177]
	v_mov_b32_e32 v176, v60
	v_mov_b32_e32 v177, v52
	v_pk_mul_f32 v[178:179], v[178:179], v[178:179]
	v_mov_b32_e32 v183, v51
	v_pk_fma_f32 v[176:177], v[176:177], v[176:177], v[178:179]
	v_mov_b32_e32 v178, v58
	v_mov_b32_e32 v179, v50
	v_pk_mul_f32 v[182:183], v[182:183], v[182:183]
	v_pk_mul_f32 v[168:169], v[46:47], v[198:199] op_sel_hi:[1,0]
	v_pk_fma_f32 v[178:179], v[178:179], v[178:179], v[182:183]
	s_nop 0
	v_pk_add_f32 v[176:177], v[176:177], v[178:179]
	s_nop 0
	v_pk_add_f32 v[174:175], v[174:175], v[176:177]
	s_nop 0
	v_add_f32_e32 v220, v174, v175
	v_add_u32_e32 v174, 0x90, v146
	v_ashrrev_i32_e32 v175, 31, v174
	v_lshlrev_b64 v[176:177], 11, v[174:175]
	v_lshl_add_u64 v[176:177], v[158:159], 0, v[176:177]
	v_mov_b64_e32 v[178:179], v[176:177]
	s_waitcnt vmcnt(2)
	ds_read_b128 v[182:185], v231 offset:16
	ds_read_b128 v[186:189], v231 offset:0
	v_lshlrev_b32_e32 v190, 16, v244
	v_and_b32_e32 v191, 0xffff0000, v244
	v_lshlrev_b32_e32 v192, 16, v245
	v_and_b32_e32 v193, 0xffff0000, v245
	v_lshlrev_b32_e32 v194, 16, v246
	v_and_b32_e32 v195, 0xffff0000, v246
	v_lshlrev_b32_e32 v196, 16, v247
	v_and_b32_e32 v197, 0xffff0000, v247
	s_mov_b32 s100, 0x58000
	v_lshl_add_u64 v[232:233], v[234:235], 0, s[100:101]
	global_load_dwordx4 v[244:247], v[232:233], off
	s_waitcnt lgkmcnt(0)
	v_pk_fma_f32 v[46:47], v[48:49], v[188:189], v[192:193]
	v_pk_fma_f32 v[48:49], v[168:169], v[186:187], v[190:191]
	v_pk_mul_f32 v[168:169], v[42:43], v[198:199] op_sel_hi:[1,0]
	v_pk_fma_f32 v[42:43], v[44:45], v[184:185], v[196:197]
	ds_read_b128 v[184:187], v231 offset:528
	ds_read_b128 v[188:191], v231 offset:512
	v_pk_fma_f32 v[44:45], v[168:169], v[182:183], v[194:195]
	s_waitcnt lgkmcnt(0)
	v_lshlrev_b32_e32 v178, 16, v248
	v_and_b32_e32 v179, 0xffff0000, v248
	v_lshlrev_b32_e32 v168, 16, v249
	v_and_b32_e32 v169, 0xffff0000, v249
	v_lshlrev_b32_e32 v192, 16, v250
	v_and_b32_e32 v193, 0xffff0000, v250
	v_lshlrev_b32_e32 v182, 16, v251
	v_and_b32_e32 v183, 0xffff0000, v251
	global_load_dwordx4 v[248:251], v[232:233], off offset:256
	s_waitcnt lgkmcnt(0)
	v_pk_fma_f32 v[182:183], v[36:37], v[186:187], v[182:183]
	s_waitcnt lgkmcnt(0)
	v_pk_fma_f32 v[178:179], v[38:39], v[188:189], v[178:179]
	v_pk_fma_f32 v[168:169], v[40:41], v[190:191], v[168:169]
	v_mov_b32_e32 v36, v49
	v_mov_b32_e32 v37, v179
	v_pk_fma_f32 v[184:185], v[34:35], v[184:185], v[192:193]
	v_mov_b32_e32 v34, v48
	v_mov_b32_e32 v35, v178
	v_pk_mul_f32 v[36:37], v[36:37], v[36:37]
	v_mov_b32_e32 v38, v47
	v_mov_b32_e32 v39, v169
	v_pk_fma_f32 v[34:35], v[34:35], v[34:35], v[36:37]
	v_mov_b32_e32 v36, v46
	v_mov_b32_e32 v37, v168
	v_pk_mul_f32 v[38:39], v[38:39], v[38:39]
	v_mov_b32_e32 v40, v43
	v_pk_fma_f32 v[36:37], v[36:37], v[36:37], v[38:39]
	v_mov_b32_e32 v38, v45
	v_mov_b32_e32 v39, v185
	v_pk_add_f32 v[34:35], v[34:35], v[36:37]
	v_mov_b32_e32 v36, v44
	v_mov_b32_e32 v37, v184
	v_pk_mul_f32 v[38:39], v[38:39], v[38:39]
	v_mov_b32_e32 v41, v183
	v_pk_fma_f32 v[36:37], v[36:37], v[36:37], v[38:39]
	v_mov_b32_e32 v38, v42
	v_mov_b32_e32 v39, v182
	v_pk_mul_f32 v[40:41], v[40:41], v[40:41]
	v_add_u32_e32 v186, 0xa0, v146
	v_pk_fma_f32 v[38:39], v[38:39], v[38:39], v[40:41]
	v_ashrrev_i32_e32 v187, 31, v186
	v_pk_add_f32 v[36:37], v[36:37], v[38:39]
	s_nop 0
	v_pk_add_f32 v[34:35], v[34:35], v[36:37]
	s_nop 0
	v_add_f32_e32 v221, v34, v35
	v_lshlrev_b64 v[34:35], 11, v[186:187]
	v_lshl_add_u64 v[188:189], v[158:159], 0, v[34:35]
	v_mov_b64_e32 v[34:35], v[188:189]
	s_waitcnt vmcnt(2)
; __device__ __forceinline__ float xhalf_sum(float x) { auto t = __builtin_amdgcn_permlane32_swap(__float_as_uint(x), __float_as_uint(x), false, false); return __uint_as_float(t[0]) + __uint_as_float(t[1]); }
;     __device__ __forceinline__ void exchange(int e, float (&sv)[2][4], float (&rv)[2][4], const Unit& u, int wr, int wc, int fr, int fq, LAS unsigned char* lds, int wid, int lane) const {
;     ...
;                 float v = sv[ai][m];
;                 { auto t1 = __builtin_amdgcn_permlane16_swap(__float_as_uint(v), __float_as_uint(v), false, false); v = __uint_as_float(t1[0]) + __uint_as_float(t1[1]); }
;                 v = xhalf_sum(v);
;                 if (fq == 0) P[(ai * HALF + wr * 64 + m * 16 + fr) * 4 + wc] = v;
;     __device__ __forceinline__ void fused(f32x4 (&acc)[2][2][4][2], const Unit& u, int wr, int wc, int fr, int fq, LAS unsigned char* lds, int wid, int lane) const {
;     ...
;                 const bf16_t* hrow = hb + (size_t)(row0 + ai * HALF + m * 16) * DM + col0;
;                 asm volatile("" : "+v"(hrow) : "v"(dep));
;                 const float r1 = rv[ai][m];
;                 float q = 0.f;
; #pragma unroll
;                 for (int bj = 0; bj < 2; ++bj) {
;                     const u32x4 hv = *(const u32x4*)(hrow + bj * HALF);
;                     const f32x4 h0 = (f32x4){__uint_as_float(hv.x << 16), __uint_as_float(hv.x & 0xffff0000u), __uint_as_float(hv.y << 16), __uint_as_float(hv.y & 0xffff0000u)};
;                     const f32x4 h1 = (f32x4){__uint_as_float(hv.z << 16), __uint_as_float(hv.z & 0xffff0000u), __uint_as_float(hv.w << 16), __uint_as_float(hv.w & 0xffff0000u)};
;                     const f32x4 gg0 = *(const f32x4*)(gpost + col0 + bj * HALF), gg1 = *(const f32x4*)(gpost + col0 + bj * HALF + 4);
;                     f32x4 x0 = h0 + acc[ai][bj][m][0] * r1 * gg0, x1 = h1 + acc[ai][bj][m][1] * r1 * gg1;
;                     acc[ai][bj][m][0] = x0; acc[ai][bj][m][1] = x1;
;                     q += ((x0[0] * x0[0] + x0[1] * x0[1]) + (x0[2] * x0[2] + x0[3] * x0[3])) + ((x1[0] * x1[0] + x1[1] * x1[1]) + (x1[2] * x1[2] + x1[3] * x1[3]));
;                 }
;                 sv[ai][m] = q;
;                 dep = q;
	ds_read_b128 v[36:39], v231 offset:16
	ds_read_b128 v[192:195], v231 offset:0
	v_lshlrev_b32_e32 v40, 16, v236
	v_and_b32_e32 v41, 0xffff0000, v236
	v_lshlrev_b32_e32 v190, 16, v237
	v_and_b32_e32 v191, 0xffff0000, v237
	v_lshlrev_b32_e32 v196, 16, v238
	v_and_b32_e32 v197, 0xffff0000, v238
	v_lshlrev_b32_e32 v198, 16, v239
	v_and_b32_e32 v199, 0xffff0000, v239
	s_waitcnt lgkmcnt(0)
	v_pk_fma_f32 v[196:197], v[26:27], v[36:37], v[196:197]
	s_waitcnt lgkmcnt(0)
	v_pk_fma_f32 v[190:191], v[32:33], v[194:195], v[190:191]
	v_pk_fma_f32 v[194:195], v[28:29], v[38:39], v[198:199]
	ds_read_b128 v[26:29], v231 offset:528
	v_pk_fma_f32 v[192:193], v[30:31], v[192:193], v[40:41]
	ds_read_b128 v[30:33], v231 offset:512
	s_waitcnt lgkmcnt(0)
	v_lshlrev_b32_e32 v34, 16, v240
	v_and_b32_e32 v35, 0xffff0000, v240
	v_lshlrev_b32_e32 v36, 16, v241
	v_and_b32_e32 v37, 0xffff0000, v241
	v_lshlrev_b32_e32 v38, 16, v242
	v_and_b32_e32 v39, 0xffff0000, v242
	v_lshlrev_b32_e32 v40, 16, v243
	v_and_b32_e32 v41, 0xffff0000, v243
	s_waitcnt lgkmcnt(0)
	v_pk_fma_f32 v[202:203], v[20:21], v[28:29], v[40:41]
	s_waitcnt lgkmcnt(0)
	v_pk_fma_f32 v[200:201], v[22:23], v[30:31], v[34:35]
	v_pk_fma_f32 v[198:199], v[24:25], v[32:33], v[36:37]
	v_mov_b32_e32 v20, v193
	v_mov_b32_e32 v21, v201
	v_pk_fma_f32 v[204:205], v[18:19], v[26:27], v[38:39]
	v_mov_b32_e32 v18, v192
	v_mov_b32_e32 v19, v200
	v_pk_mul_f32 v[20:21], v[20:21], v[20:21]
	v_mov_b32_e32 v22, v191
	v_mov_b32_e32 v23, v199
	v_pk_fma_f32 v[18:19], v[18:19], v[18:19], v[20:21]
	v_mov_b32_e32 v20, v190
	v_mov_b32_e32 v21, v198
	v_pk_mul_f32 v[22:23], v[22:23], v[22:23]
	v_mov_b32_e32 v24, v195
	v_pk_fma_f32 v[20:21], v[20:21], v[20:21], v[22:23]
	v_mov_b32_e32 v22, v197
	v_mov_b32_e32 v23, v205
	v_pk_add_f32 v[18:19], v[18:19], v[20:21]
	v_mov_b32_e32 v20, v196
	v_mov_b32_e32 v21, v204
	v_pk_mul_f32 v[22:23], v[22:23], v[22:23]
	v_mov_b32_e32 v25, v203
	v_pk_fma_f32 v[20:21], v[20:21], v[20:21], v[22:23]
	v_mov_b32_e32 v22, v194
	v_mov_b32_e32 v23, v202
	v_pk_mul_f32 v[24:25], v[24:25], v[24:25]
	s_nop 0
	v_pk_fma_f32 v[22:23], v[22:23], v[22:23], v[24:25]
	s_nop 0
	v_pk_add_f32 v[20:21], v[20:21], v[22:23]
	s_nop 0
	v_pk_add_f32 v[18:19], v[18:19], v[20:21]
	s_nop 0
	v_add_f32_e32 v154, v18, v19
	v_lshlrev_b64 v[18:19], 11, v[206:207]
	v_lshl_add_u64 v[158:159], v[158:159], 0, v[18:19]
	v_mov_b64_e32 v[18:19], v[158:159]
	ds_read_b128 v[30:33], v231 offset:16
	ds_read_b128 v[34:37], v231 offset:0
	ds_read_b128 v[18:21], v231 offset:528
	ds_read_b128 v[22:25], v231 offset:512
	s_nop 0
	v_mov_b32_e32 v156, v216
	s_nop 1
	v_permlane16_swap_b32_e32 v216, v156
	v_add_f32_e32 v156, v216, v156
	v_mov_b32_e32 v157, v156
	s_nop 1
	v_permlane32_swap_b32_e32 v156, v157
	s_and_saveexec_b64 s[10:11], s[4:5]
	v_add_f32_e32 v156, v156, v157
	ds_write_b32 v212, v156
	s_or_b64 exec, exec, s[10:11]
	v_mov_b32_e32 v156, v217
	s_nop 1
	v_permlane16_swap_b32_e32 v217, v156
	v_add_f32_e32 v156, v217, v156
	v_mov_b32_e32 v157, v156
	s_nop 1
	v_permlane32_swap_b32_e32 v156, v157
	s_and_saveexec_b64 s[10:11], s[4:5]
	v_add_f32_e32 v156, v156, v157
	ds_write_b32 v212, v156 offset:256
	s_or_b64 exec, exec, s[10:11]
	v_mov_b32_e32 v156, v218
	s_nop 1
	v_permlane16_swap_b32_e32 v218, v156
	v_add_f32_e32 v156, v218, v156
	v_mov_b32_e32 v157, v156
	s_nop 1
	v_permlane32_swap_b32_e32 v156, v157
	s_and_saveexec_b64 s[10:11], s[4:5]
	v_add_f32_e32 v156, v156, v157
	ds_write_b32 v212, v156 offset:512
	s_or_b64 exec, exec, s[10:11]
	v_mov_b32_e32 v156, v219
	s_nop 1
	v_permlane16_swap_b32_e32 v219, v156
	v_add_f32_e32 v156, v219, v156
	v_mov_b32_e32 v157, v156
	s_nop 1
	v_permlane32_swap_b32_e32 v156, v157
	s_and_saveexec_b64 s[10:11], s[4:5]
	v_add_f32_e32 v156, v156, v157
	ds_write_b32 v212, v156 offset:768
	s_or_b64 exec, exec, s[10:11]
	v_mov_b32_e32 v156, v220
	s_nop 1
	v_permlane16_swap_b32_e32 v220, v156
	v_add_f32_e32 v156, v220, v156
	v_mov_b32_e32 v157, v156
	s_nop 1
	v_permlane32_swap_b32_e32 v156, v157
	s_and_saveexec_b64 s[10:11], s[4:5]
	v_add_f32_e32 v156, v156, v157
	ds_write_b32 v212, v156 offset:2048
	s_or_b64 exec, exec, s[10:11]
	v_mov_b32_e32 v156, v221
	s_nop 1
	v_permlane16_swap_b32_e32 v221, v156
	v_add_f32_e32 v156, v221, v156
	v_mov_b32_e32 v157, v156
	s_nop 1
	v_permlane32_swap_b32_e32 v156, v157
	s_and_saveexec_b64 s[10:11], s[4:5]
	v_add_f32_e32 v156, v156, v157
	ds_write_b32 v212, v156 offset:2304
	s_or_b64 exec, exec, s[10:11]
	v_mov_b32_e32 v156, v154
	s_nop 1
	v_permlane16_swap_b32_e32 v154, v156
	v_add_f32_e32 v154, v154, v156
	v_mov_b32_e32 v156, v154
	s_nop 1
	v_permlane32_swap_b32_e32 v154, v156
	s_and_saveexec_b64 s[10:11], s[4:5]
	v_add_f32_e32 v154, v154, v156
	ds_write_b32 v212, v154 offset:2560
	s_or_b64 exec, exec, s[10:11]
	v_mov_b32_e32 v154, v155
	s_waitcnt vmcnt(0) lgkmcnt(0)
; #define LAS __attribute__((address_space(3)))
; __device__ __forceinline__ float xhalf_sum(float x) { auto t = __builtin_amdgcn_permlane32_swap(__float_as_uint(x), __float_as_uint(x), false, false); return __uint_as_float(t[0]) + __uint_as_float(t[1]); }
;     __device__ __forceinline__ void exchange(int e, float (&sv)[2][4], float (&rv)[2][4], const Unit& u, int wr, int wc, int fr, int fq, LAS unsigned char* lds, int wid, int lane) const {
;     ...
;                 float v = sv[ai][m];
;                 { auto t1 = __builtin_amdgcn_permlane16_swap(__float_as_uint(v), __float_as_uint(v), false, false); v = __uint_as_float(t1[0]) + __uint_as_float(t1[1]); }
;                 v = xhalf_sum(v);
;                 if (fq == 0) P[(ai * HALF + wr * 64 + m * 16 + fr) * 4 + wc] = v;
;             }
;         asm volatile("s_waitcnt lgkmcnt(0)" ::: "memory"); __builtin_amdgcn_s_barrier(); asm volatile("" ::: "memory");
;         const int tid = wid * 64 + lane;
;         if (tid < 256) {
;             const f32x4 pp = *(const LAS f32x4*)(P + tid * 4);
;             __hip_atomic_store(xbuf + ((size_t)u.pm * 256 + tid) * 4 + u.pn, (pp[0] + pp[1]) + (pp[2] + pp[3]), __ATOMIC_RELAXED, __HIP_MEMORY_SCOPE_AGENT);
;         }
;         asm volatile("s_waitcnt vmcnt(0)" ::: "memory");
;         if (wid < 4 && lane == 0) __hip_atomic_fetch_add(cnt, 1u, __ATOMIC_RELAXED, __HIP_MEMORY_SCOPE_AGENT);
;         if (wid == 0) {
;             unsigned sp = 0;
;             while ((unsigned)__builtin_amdgcn_readfirstlane(__hip_atomic_load(cnt, __ATOMIC_RELAXED, __HIP_MEMORY_SCOPE_AGENT)) < 16u) { __builtin_amdgcn_s_sleep(2); if (++sp > (1u << 22)) break; }
;             __builtin_amdgcn_fence(__ATOMIC_ACQUIRE, "agent");
;         }
;     __device__ __forceinline__ void fused(f32x4 (&acc)[2][2][4][2], const Unit& u, int wr, int wc, int fr, int fq, LAS unsigned char* lds, int wid, int lane) const {
;     ...
;                     f32x4 x0 = h0 + acc[ai][bj][m][0] * r1 * gg0, x1 = h1 + acc[ai][bj][m][1] * r1 * gg1;
;                     acc[ai][bj][m][0] = x0; acc[ai][bj][m][1] = x1;
;                     q += ((x0[0] * x0[0] + x0[1] * x0[1]) + (x0[2] * x0[2] + x0[3] * x0[3])) + ((x1[0] * x1[0] + x1[1] * x1[1]) + (x1[2] * x1[2] + x1[3] * x1[3]));
;                 }
;                 sv[ai][m] = q;
;                 dep = q;
	v_lshlrev_b32_e32 v156, 16, v244
	v_and_b32_e32 v157, 0xffff0000, v244
	v_lshlrev_b32_e32 v38, 16, v245
	v_and_b32_e32 v39, 0xffff0000, v245
	v_pk_mul_f32 v[16:17], v[16:17], v[154:155] op_sel_hi:[1,0]
	v_pk_mul_f32 v[218:219], v[14:15], v[154:155] op_sel_hi:[1,0]
	v_lshlrev_b32_e32 v216, 16, v246
	v_and_b32_e32 v217, 0xffff0000, v246
	v_lshlrev_b32_e32 v40, 16, v247
	v_and_b32_e32 v41, 0xffff0000, v247
	v_pk_fma_f32 v[14:15], v[16:17], v[36:37], v[38:39]
	v_pk_fma_f32 v[16:17], v[218:219], v[34:35], v[156:157]
	v_pk_mul_f32 v[12:13], v[12:13], v[154:155] op_sel_hi:[1,0]
	v_pk_mul_f32 v[34:35], v[10:11], v[154:155] op_sel_hi:[1,0]
	v_pk_fma_f32 v[10:11], v[12:13], v[32:33], v[40:41]
	v_pk_fma_f32 v[12:13], v[34:35], v[30:31], v[216:217]
	v_mul_f32_e32 v30, v17, v17
	v_mul_f32_e32 v31, v15, v15
	v_fmac_f32_e32 v30, v16, v16
	v_fmac_f32_e32 v31, v14, v14
	v_add_f32_e32 v30, v30, v31
	v_mul_f32_e32 v31, v13, v13
	v_mul_f32_e32 v32, v11, v11
	v_fmac_f32_e32 v31, v12, v12
	v_fmac_f32_e32 v32, v10, v10
	v_add_f32_e32 v31, v31, v32
	v_add_f32_e32 v36, v30, v31
	v_lshlrev_b32_e32 v30, 16, v248
	v_and_b32_e32 v31, 0xffff0000, v248
	v_lshlrev_b32_e32 v26, 16, v249
	v_and_b32_e32 v27, 0xffff0000, v249
	v_pk_mul_f32 v[8:9], v[8:9], v[154:155] op_sel_hi:[1,0]
	v_pk_mul_f32 v[34:35], v[6:7], v[154:155] op_sel_hi:[1,0]
	v_lshlrev_b32_e32 v32, 16, v250
	v_and_b32_e32 v33, 0xffff0000, v250
	v_lshlrev_b32_e32 v28, 16, v251
	v_and_b32_e32 v29, 0xffff0000, v251
	v_pk_fma_f32 v[6:7], v[8:9], v[24:25], v[26:27]
	v_pk_fma_f32 v[8:9], v[34:35], v[22:23], v[30:31]
	v_pk_mul_f32 v[4:5], v[4:5], v[154:155] op_sel_hi:[1,0]
	v_pk_mul_f32 v[22:23], v[2:3], v[154:155] op_sel_hi:[1,0]
	v_pk_fma_f32 v[2:3], v[4:5], v[20:21], v[28:29]
	v_pk_fma_f32 v[4:5], v[22:23], v[18:19], v[32:33]
	v_mul_f32_e32 v18, v9, v9
	v_mul_f32_e32 v19, v7, v7
	v_fmac_f32_e32 v18, v8, v8
	v_fmac_f32_e32 v19, v6, v6
	v_add_f32_e32 v18, v18, v19
	v_mul_f32_e32 v19, v5, v5
	v_mul_f32_e32 v20, v3, v3
	v_fmac_f32_e32 v19, v4, v4
	v_fmac_f32_e32 v20, v2, v2
	v_add_f32_e32 v19, v19, v20
	v_add_f32_e32 v18, v18, v19
	v_add_f32_e32 v18, v36, v18
	v_mov_b32_e32 v19, v18
	s_nop 1
	v_permlane16_swap_b32_e32 v18, v19
	v_add_f32_e32 v18, v18, v19
	v_mov_b32_e32 v19, v18
	s_nop 1
	v_permlane32_swap_b32_e32 v18, v19
	s_and_saveexec_b64 s[10:11], s[4:5]
	v_add_f32_e32 v18, v18, v19
	ds_write_b32 v212, v18 offset:2816
	s_or_b64 exec, exec, s[10:11]
	s_waitcnt lgkmcnt(0)
	s_barrier
	s_and_saveexec_b64 s[10:11], s[6:7]
	s_cbranch_execz .LBB0_1452
	ds_read_b128 v[18:21], v215
	s_lshl_b64 s[42:43], s[28:29], 12
	v_lshl_add_u64 v[22:23], v[140:141], 0, s[42:43]
	s_mov_b32 s100, s59
	v_lshl_add_u64 v[250:251], v[22:23], 0, s[42:43]
	v_mov_b32_e32 v249, 0x880000
	v_lshl_add_u32 v248, v222, 4, v249
	v_mov_b32_e32 v249, 0
	v_lshl_add_u64 v[250:251], v[248:249], 0, v[250:251]
	s_ashr_i32 s27, s26, 31
	v_lshl_add_u64 v[22:23], s[26:27], 2, v[22:23]
	v_lshl_add_u64 v[248:249], s[26:27], 3, v[250:251]
	s_waitcnt lgkmcnt(0)
	v_mov_b32_e32 v24, v19
	v_mov_b32_e32 v25, v20
	v_mov_b32_e32 v19, v21
	v_pk_add_f32 v[18:19], v[24:25], v[18:19]
	s_nop 0
	v_pk_add_f32 v[18:19], v[18:19], v[18:19] op_sel:[0,1] op_sel_hi:[1,0]
	v_xor_b32_e32 v19, s100, v18
	global_store_dwordx2 v[248:249], v[18:19], off sc1
.LBB0_1452:
	s_or_b64 exec, exec, s[10:11]
	s_add_u32 s10, s59, s40
	s_addc_u32 s11, s60, s41
	s_and_saveexec_b64 s[40:41], s[18:19]
	s_cbranch_execz .LBB0_1455
	s_mov_b64 s[42:43], exec
	v_mbcnt_lo_u32_b32 v18, s42, 0
	v_mbcnt_hi_u32_b32 v18, s43, v18
	v_cmp_eq_u32_e32 vcc, 0, v18
	s_and_b64 s[64:65], exec, vcc
	s_mov_b64 exec, s[64:65]
	s_cbranch_execz .LBB0_1455
	s_bcnt1_i32_b64 s27, s[42:43]
	v_mov_b32_e32 v18, s27
.LBB0_1455:
	s_or_b64 exec, exec, s[40:41]
	s_and_b64 vcc, exec, s[8:9]
	s_cbranch_vccnz .LBB0_1465
	s_branch .LBB0_1465

;     __device__ __forceinline__ void exchange(int e, float (&sv)[2][4], float (&rv)[2][4], const Unit& u, int wr, int wc, int fr, int fq, LAS unsigned char* lds, int wid, int lane) const {
;     ...
;         asm volatile("s_waitcnt vmcnt(0) lgkmcnt(0)" ::: "memory"); __builtin_amdgcn_s_barrier(); asm volatile("" ::: "memory");
;         if (tid < 256) {
;             const float* sl = xbuf + ((size_t)u.pm * 256 + tid) * 4;
;             const float t0 = __hip_atomic_load(sl + 0, __ATOMIC_RELAXED, __HIP_MEMORY_SCOPE_AGENT), t1 = __hip_atomic_load(sl + 1, __ATOMIC_RELAXED, __HIP_MEMORY_SCOPE_AGENT);
.LBB0_1465:
	s_waitcnt lgkmcnt(0)
	s_barrier
	s_and_saveexec_b64 s[10:11], s[6:7]
	s_cbranch_execz .LBB0_1467
	s_lshl_b64 s[8:9], s[28:29], 12
	v_lshl_add_u64 v[18:19], v[140:141], 0, s[8:9]
	v_lshl_add_u64 v[250:251], v[18:19], 0, s[8:9]
	v_mov_b32_e32 v249, 0x880000
	v_lshl_add_u32 v248, v222, 4, v249
	v_mov_b32_e32 v249, 0
	v_lshl_add_u64 v[250:251], v[248:249], 0, v[250:251]
	s_mov_b32 s101, 0x4000

;     __device__ __forceinline__ void exchange(int e, float (&sv)[2][4], float (&rv)[2][4], const Unit& u, int wr, int wc, int fr, int fq, LAS unsigned char* lds, int wid, int lane) const {
;     ...
;             const float t0 = __hip_atomic_load(sl + 0, __ATOMIC_RELAXED, __HIP_MEMORY_SCOPE_AGENT), t1 = __hip_atomic_load(sl + 1, __ATOMIC_RELAXED, __HIP_MEMORY_SCOPE_AGENT);
;             const float t2 = __hip_atomic_load(sl + 2, __ATOMIC_RELAXED, __HIP_MEMORY_SCOPE_AGENT), t3 = __hip_atomic_load(sl + 3, __ATOMIC_RELAXED, __HIP_MEMORY_SCOPE_AGENT);
;             Sx[tid] = 1.0f / sqrtf(((t0 + t1) + (t2 + t3)) * (1.0f / 1024.0f) + RMS_EPS);
.Lx_rdy3:
	s_mov_b32 s8, 0xf800000
	v_mov_b32_e32 v20, v236
	v_mov_b32_e32 v22, v238
	v_mov_b32_e32 v21, v240
	v_mov_b32_e32 v23, v242
	v_pk_add_f32 v[18:19], v[20:21], v[22:23]
	s_nop 0
	v_add_f32_e32 v18, v18, v19
	v_fmamk_f32 v18, v18, 0x3a800000, v228
	v_mul_f32_e32 v19, 0x4f800000, v18
	v_cmp_gt_f32_e32 vcc, s8, v18
	s_nop 1
	v_cndmask_b32_e32 v18, v18, v19, vcc
	v_sqrt_f32_e32 v19, v18
	s_nop 0
	v_add_u32_e32 v20, -1, v19
	v_add_u32_e32 v21, 1, v19
	v_fma_f32 v22, -v20, v19, v18
	v_fma_f32 v23, -v21, v19, v18
	v_cmp_ge_f32_e64 s[8:9], 0, v22
	s_nop 1
	v_cndmask_b32_e64 v19, v19, v20, s[8:9]
	v_cmp_lt_f32_e64 s[8:9], 0, v23
	s_nop 1
	v_cndmask_b32_e64 v19, v19, v21, s[8:9]
	v_mul_f32_e32 v20, 0x37800000, v19
	v_cndmask_b32_e32 v19, v19, v20, vcc
	v_cmp_class_f32_e32 vcc, v18, v227
	s_nop 1
	v_cndmask_b32_e32 v18, v19, v18, vcc
	v_div_scale_f32 v19, s[8:9], v18, v18, 1.0
	v_rcp_f32_e32 v20, v19
	v_div_scale_f32 v21, vcc, 1.0, v18, 1.0
	v_fma_f32 v22, -v19, v20, 1.0
	v_fmac_f32_e32 v20, v22, v20
	v_mul_f32_e32 v22, v21, v20
	v_fma_f32 v23, -v19, v22, v21
	v_fmac_f32_e32 v22, v23, v20
	v_fma_f32 v19, -v19, v22, v21
	v_div_fmas_f32 v19, v19, v20, v22
	v_div_fixup_f32 v18, v19, v18, 1.0
	ds_write_b32 v209, v18

; __device__ __forceinline__ float xhalf_sum(float x) { auto t = __builtin_amdgcn_permlane32_swap(__float_as_uint(x), __float_as_uint(x), false, false); return __uint_as_float(t[0]) + __uint_as_float(t[1]); }
;     __device__ __forceinline__ void exchange(int e, float (&sv)[2][4], float (&rv)[2][4], const Unit& u, int wr, int wc, int fr, int fq, LAS unsigned char* lds, int wid, int lane) const {
;     ...
;                 float v = sv[ai][m];
;                 { auto t1 = __builtin_amdgcn_permlane16_swap(__float_as_uint(v), __float_as_uint(v), false, false); v = __uint_as_float(t1[0]) + __uint_as_float(t1[1]); }
;                 v = xhalf_sum(v);
;                 if (fq == 0) P[(ai * HALF + wr * 64 + m * 16 + fr) * 4 + wc] = v;
;     __device__ __forceinline__ void fused(f32x4 (&acc)[2][2][4][2], const Unit& u, int wr, int wc, int fr, int fq, LAS unsigned char* lds, int wid, int lane) const {
;     ...
;         for (int ai = 0; ai < 2; ++ai)
; #pragma unroll
;             for (int m = 0; m < 4; ++m) {
;                 float q = 0.f;
; #pragma unroll
;                 for (int bj = 0; bj < 2; ++bj)
; #pragma unroll
;                     for (int n = 0; n < 2; ++n) { const f32x4 x = acc[ai][bj][m][n]; q += (x[0] * x[0] + x[1] * x[1]) + (x[2] * x[2] + x[3] * x[3]); }
;                 sv[ai][m] = q;
;             }
;         exchange(0, sv, rv, u, wr, wc, fr, fq, lds, wid, lane);
.LBB0_1635:
	v_mul_f32_e32 v146, v27, v27
	v_mul_f32_e32 v147, v29, v29
	v_fmac_f32_e32 v146, v26, v26
	v_fmac_f32_e32 v147, v28, v28
	v_add_f32_e32 v146, v146, v147
	v_mul_f32_e32 v147, v31, v31
	v_mul_f32_e32 v148, v33, v33
	v_fmac_f32_e32 v147, v30, v30
	v_fmac_f32_e32 v148, v32, v32
	v_add_f32_e32 v147, v147, v148
	v_add_f32_e32 v146, v146, v147
	v_mul_f32_e32 v147, v43, v43
	v_mul_f32_e32 v148, v45, v45
	v_fmac_f32_e32 v147, v42, v42
	v_fmac_f32_e32 v148, v44, v44
	v_add_f32_e32 v147, v147, v148
	v_add_f32_e32 v146, v146, v147
	v_mul_f32_e32 v147, v47, v47
	v_mul_f32_e32 v148, v49, v49
	v_fmac_f32_e32 v147, v46, v46
	v_fmac_f32_e32 v148, v48, v48
	v_add_f32_e32 v147, v147, v148
	v_add_f32_e32 v146, v146, v147
	v_mov_b32_e32 v147, v146
	s_nop 1
	v_permlane16_swap_b32_e32 v146, v147
	v_add_f32_e32 v146, v146, v147
	v_mov_b32_e32 v147, v146
	s_nop 1
	v_permlane32_swap_b32_e32 v146, v147
	s_and_saveexec_b64 s[8:9], s[4:5]
	v_add_f32_e32 v146, v146, v147
	ds_write_b32 v193, v146
	s_or_b64 exec, exec, s[8:9]
	v_mul_f32_e32 v146, v59, v59
	v_mul_f32_e32 v147, v61, v61
	v_fmac_f32_e32 v146, v58, v58
	v_fmac_f32_e32 v147, v60, v60
	v_add_f32_e32 v146, v146, v147
	v_mul_f32_e32 v147, v63, v63
	v_mul_f32_e32 v148, v65, v65
	v_fmac_f32_e32 v147, v62, v62
	v_fmac_f32_e32 v148, v64, v64
	v_add_f32_e32 v147, v147, v148
	v_add_f32_e32 v146, v146, v147
	v_mul_f32_e32 v147, v75, v75
	v_mul_f32_e32 v148, v77, v77
	v_fmac_f32_e32 v147, v74, v74
	v_fmac_f32_e32 v148, v76, v76
	v_add_f32_e32 v147, v147, v148
	v_add_f32_e32 v146, v146, v147
	v_mul_f32_e32 v147, v79, v79
	v_mul_f32_e32 v148, v81, v81
	v_fmac_f32_e32 v147, v78, v78
	v_fmac_f32_e32 v148, v80, v80
	v_add_f32_e32 v147, v147, v148
	v_add_f32_e32 v146, v146, v147
	v_mov_b32_e32 v147, v146
	s_nop 1
	v_permlane16_swap_b32_e32 v146, v147
	v_add_f32_e32 v146, v146, v147
	v_mov_b32_e32 v147, v146
	s_nop 1
	v_permlane32_swap_b32_e32 v146, v147
	s_and_saveexec_b64 s[8:9], s[4:5]
	v_add_f32_e32 v146, v146, v147
	ds_write_b32 v193, v146 offset:256
	s_or_b64 exec, exec, s[8:9]
	v_mul_f32_e32 v146, v91, v91
	v_mul_f32_e32 v147, v93, v93
	v_fmac_f32_e32 v146, v90, v90
	v_fmac_f32_e32 v147, v92, v92
	v_add_f32_e32 v146, v146, v147
	v_mul_f32_e32 v147, v95, v95
	v_mul_f32_e32 v148, v97, v97
	v_fmac_f32_e32 v147, v94, v94
	v_fmac_f32_e32 v148, v96, v96
	v_add_f32_e32 v147, v147, v148
	v_add_f32_e32 v146, v146, v147
	v_mul_f32_e32 v147, v107, v107
	v_mul_f32_e32 v148, v109, v109
	v_fmac_f32_e32 v147, v106, v106
	v_fmac_f32_e32 v148, v108, v108
	v_add_f32_e32 v147, v147, v148
	v_add_f32_e32 v146, v146, v147
	v_mul_f32_e32 v147, v111, v111
	v_mul_f32_e32 v148, v113, v113
	v_fmac_f32_e32 v147, v110, v110
	v_fmac_f32_e32 v148, v112, v112
	v_add_f32_e32 v147, v147, v148
	v_add_f32_e32 v146, v146, v147
	v_mov_b32_e32 v147, v146
	s_nop 1
	v_permlane16_swap_b32_e32 v146, v147
	v_add_f32_e32 v146, v146, v147
	v_mov_b32_e32 v147, v146
	s_nop 1
	v_permlane32_swap_b32_e32 v146, v147
	s_and_saveexec_b64 s[8:9], s[4:5]
	v_add_f32_e32 v146, v146, v147
	ds_write_b32 v193, v146 offset:512
	s_or_b64 exec, exec, s[8:9]
	v_mul_f32_e32 v146, v115, v115
	v_mul_f32_e32 v147, v117, v117
	v_fmac_f32_e32 v146, v114, v114
	v_fmac_f32_e32 v147, v116, v116
	v_add_f32_e32 v146, v146, v147
	v_mul_f32_e32 v147, v119, v119
	v_mul_f32_e32 v148, v121, v121
	v_fmac_f32_e32 v147, v118, v118
	v_fmac_f32_e32 v148, v120, v120
	v_add_f32_e32 v147, v147, v148
	v_add_f32_e32 v146, v146, v147
	v_mul_f32_e32 v147, v127, v127
	v_mul_f32_e32 v148, v129, v129
	v_fmac_f32_e32 v147, v126, v126
	v_fmac_f32_e32 v148, v128, v128
	v_add_f32_e32 v147, v147, v148
	v_add_f32_e32 v146, v146, v147
	v_mul_f32_e32 v147, v123, v123
	v_mul_f32_e32 v148, v125, v125
	v_fmac_f32_e32 v147, v122, v122
	v_fmac_f32_e32 v148, v124, v124
	v_add_f32_e32 v147, v147, v148
	v_add_f32_e32 v146, v146, v147
	v_mov_b32_e32 v147, v146
	s_nop 1
	v_permlane16_swap_b32_e32 v146, v147
	v_add_f32_e32 v146, v146, v147
	v_mov_b32_e32 v147, v146
	s_nop 1
	v_permlane32_swap_b32_e32 v146, v147
	s_and_saveexec_b64 s[8:9], s[4:5]
	v_add_f32_e32 v146, v146, v147
	ds_write_b32 v193, v146 offset:768
	s_or_b64 exec, exec, s[8:9]
	v_mul_f32_e32 v146, v103, v103
	v_mul_f32_e32 v147, v105, v105
	v_fmac_f32_e32 v146, v102, v102
	v_fmac_f32_e32 v147, v104, v104
	v_add_f32_e32 v146, v146, v147
	v_mul_f32_e32 v147, v99, v99
	v_mul_f32_e32 v148, v101, v101
	v_fmac_f32_e32 v147, v98, v98
	v_fmac_f32_e32 v148, v100, v100
	v_add_f32_e32 v147, v147, v148
	v_add_f32_e32 v146, v146, v147
	v_mul_f32_e32 v147, v87, v87
	v_mul_f32_e32 v148, v89, v89
	v_fmac_f32_e32 v147, v86, v86
	v_fmac_f32_e32 v148, v88, v88
	v_add_f32_e32 v147, v147, v148
	v_add_f32_e32 v146, v146, v147
	v_mul_f32_e32 v147, v83, v83
	v_mul_f32_e32 v148, v85, v85
	v_fmac_f32_e32 v147, v82, v82
	v_fmac_f32_e32 v148, v84, v84
	v_add_f32_e32 v147, v147, v148
	v_add_f32_e32 v146, v146, v147
	v_mov_b32_e32 v147, v146
	s_nop 1
	v_permlane16_swap_b32_e32 v146, v147
; #define LAS __attribute__((address_space(3)))
;     __device__ __forceinline__ void exchange(int e, float (&sv)[2][4], float (&rv)[2][4], const Unit& u, int wr, int wc, int fr, int fq, LAS unsigned char* lds, int wid, int lane) const {
;     ...
;                 if (fq == 0) P[(ai * HALF + wr * 64 + m * 16 + fr) * 4 + wc] = v;
;             }
;         asm volatile("s_waitcnt lgkmcnt(0)" ::: "memory"); __builtin_amdgcn_s_barrier(); asm volatile("" ::: "memory");
;         const int tid = wid * 64 + lane;
;         if (tid < 256) {
;             const f32x4 pp = *(const LAS f32x4*)(P + tid * 4);
;             __hip_atomic_store(xbuf + ((size_t)u.pm * 256 + tid) * 4 + u.pn, (pp[0] + pp[1]) + (pp[2] + pp[3]), __ATOMIC_RELAXED, __HIP_MEMORY_SCOPE_AGENT);
;         }
;         asm volatile("s_waitcnt vmcnt(0)" ::: "memory");
;         if (wid < 4 && lane == 0) __hip_atomic_fetch_add(cnt, 1u, __ATOMIC_RELAXED, __HIP_MEMORY_SCOPE_AGENT);
;         if (wid == 0) {
;             unsigned sp = 0;
;             while ((unsigned)__builtin_amdgcn_readfirstlane(__hip_atomic_load(cnt, __ATOMIC_RELAXED, __HIP_MEMORY_SCOPE_AGENT)) < 16u) { __builtin_amdgcn_s_sleep(2); if (++sp > (1u << 22)) break; }
;             __builtin_amdgcn_fence(__ATOMIC_ACQUIRE, "agent");
;         }
	v_add_f32_e32 v146, v146, v147
	v_mov_b32_e32 v147, v146
	s_nop 1
	v_permlane32_swap_b32_e32 v146, v147
	s_and_saveexec_b64 s[8:9], s[4:5]
	v_add_f32_e32 v146, v146, v147
	ds_write_b32 v193, v146 offset:2048
	s_or_b64 exec, exec, s[8:9]
	v_mul_f32_e32 v146, v71, v71
	v_mul_f32_e32 v147, v73, v73
	v_fmac_f32_e32 v146, v70, v70
	v_fmac_f32_e32 v147, v72, v72
	v_add_f32_e32 v146, v146, v147
	v_mul_f32_e32 v147, v67, v67
	v_mul_f32_e32 v148, v69, v69
	v_fmac_f32_e32 v147, v66, v66
	v_fmac_f32_e32 v148, v68, v68
	v_add_f32_e32 v147, v147, v148
	v_add_f32_e32 v146, v146, v147
	v_mul_f32_e32 v147, v55, v55
	v_mul_f32_e32 v148, v57, v57
	v_fmac_f32_e32 v147, v54, v54
	v_fmac_f32_e32 v148, v56, v56
	v_add_f32_e32 v147, v147, v148
	v_add_f32_e32 v146, v146, v147
	v_mul_f32_e32 v147, v51, v51
	v_mul_f32_e32 v148, v53, v53
	v_fmac_f32_e32 v147, v50, v50
	v_fmac_f32_e32 v148, v52, v52
	v_add_f32_e32 v147, v147, v148
	v_add_f32_e32 v146, v146, v147
	v_mov_b32_e32 v147, v146
	s_nop 1
	v_permlane16_swap_b32_e32 v146, v147
	v_add_f32_e32 v146, v146, v147
	v_mov_b32_e32 v147, v146
	s_nop 1
	v_permlane32_swap_b32_e32 v146, v147
	s_and_saveexec_b64 s[8:9], s[4:5]
	v_add_f32_e32 v146, v146, v147
	ds_write_b32 v193, v146 offset:2304
	s_or_b64 exec, exec, s[8:9]
	v_mul_f32_e32 v146, v39, v39
	v_mul_f32_e32 v147, v41, v41
	v_fmac_f32_e32 v146, v38, v38
	v_fmac_f32_e32 v147, v40, v40
	v_add_f32_e32 v146, v146, v147
	v_mul_f32_e32 v147, v35, v35
	v_mul_f32_e32 v148, v37, v37
	v_fmac_f32_e32 v147, v34, v34
	v_fmac_f32_e32 v148, v36, v36
	v_add_f32_e32 v147, v147, v148
	v_add_f32_e32 v146, v146, v147
	v_mul_f32_e32 v147, v23, v23
	v_mul_f32_e32 v148, v25, v25
	v_fmac_f32_e32 v147, v22, v22
	v_fmac_f32_e32 v148, v24, v24
	v_add_f32_e32 v147, v147, v148
	v_add_f32_e32 v146, v146, v147
	v_mul_f32_e32 v147, v19, v19
	v_mul_f32_e32 v148, v21, v21
	v_fmac_f32_e32 v147, v18, v18
	v_fmac_f32_e32 v148, v20, v20
	v_add_f32_e32 v147, v147, v148
	v_add_f32_e32 v146, v146, v147
	v_mov_b32_e32 v147, v146
	s_nop 1
	v_permlane16_swap_b32_e32 v146, v147
	v_add_f32_e32 v146, v146, v147
	v_mov_b32_e32 v147, v146
	s_nop 1
	v_permlane32_swap_b32_e32 v146, v147
	s_and_saveexec_b64 s[8:9], s[4:5]
	v_add_f32_e32 v146, v146, v147
	ds_write_b32 v193, v146 offset:2560
	s_or_b64 exec, exec, s[8:9]
	v_mul_f32_e32 v146, v15, v15
	v_mul_f32_e32 v147, v17, v17
	v_fmac_f32_e32 v146, v14, v14
	v_fmac_f32_e32 v147, v16, v16
	v_add_f32_e32 v146, v146, v147
	v_mul_f32_e32 v147, v11, v11
	v_mul_f32_e32 v148, v13, v13
	v_fmac_f32_e32 v147, v10, v10
	v_fmac_f32_e32 v148, v12, v12
	v_add_f32_e32 v147, v147, v148
	v_add_f32_e32 v146, v146, v147
	v_mul_f32_e32 v147, v7, v7
	v_mul_f32_e32 v148, v9, v9
	v_fmac_f32_e32 v147, v6, v6
	v_fmac_f32_e32 v148, v8, v8
	v_add_f32_e32 v147, v147, v148
	v_add_f32_e32 v146, v146, v147
	v_mul_f32_e32 v147, v3, v3
	v_mul_f32_e32 v148, v5, v5
	v_fmac_f32_e32 v147, v2, v2
	v_fmac_f32_e32 v148, v4, v4
	v_add_f32_e32 v147, v147, v148
	v_add_f32_e32 v146, v146, v147
	v_mov_b32_e32 v147, v146
	s_nop 1
	v_permlane16_swap_b32_e32 v146, v147
	v_add_f32_e32 v146, v146, v147
	v_mov_b32_e32 v147, v146
	s_nop 1
	v_permlane32_swap_b32_e32 v146, v147
	s_and_saveexec_b64 s[8:9], s[4:5]
	v_add_f32_e32 v146, v146, v147
	ds_write_b32 v193, v146 offset:2816
	s_or_b64 exec, exec, s[8:9]
	s_waitcnt lgkmcnt(0)
	s_barrier
	s_ashr_i32 s37, s36, 31
	s_and_saveexec_b64 s[8:9], s[6:7]
	s_cbranch_execz .LBB0_1653
	v_add_u32_e32 v146, 0, v189
	v_add_u32_e32 v146, 0x20000, v146
	ds_read_b128 v[146:149], v146
	s_lshl_b64 s[10:11], s[36:37], 12
	v_lshl_add_u64 v[150:151], v[138:139], 0, s[10:11]
	s_mov_b32 s100, s58
	v_lshl_add_u64 v[250:251], v[150:151], 0, s[10:11]
	v_mov_b32_e32 v249, 0x800000
	v_lshl_add_u32 v248, v222, 4, v249
	v_mov_b32_e32 v249, 0
	v_lshl_add_u64 v[250:251], v[248:249], 0, v[250:251]
	s_ashr_i32 s35, s34, 31
	v_lshl_add_u64 v[150:151], s[34:35], 2, v[150:151]
	v_lshl_add_u64 v[248:249], s[34:35], 3, v[250:251]
	s_waitcnt lgkmcnt(0)
	v_mov_b32_e32 v152, v147
	v_mov_b32_e32 v153, v148
	v_mov_b32_e32 v147, v149
	v_pk_add_f32 v[146:147], v[152:153], v[146:147]
	s_nop 0
	v_pk_add_f32 v[146:147], v[146:147], v[146:147] op_sel:[0,1] op_sel_hi:[1,0]
	v_xor_b32_e32 v147, s100, v146
	global_store_dwordx2 v[248:249], v[146:147], off sc1
.LBB0_1653:
	s_or_b64 exec, exec, s[8:9]
	s_lshl_b64 s[42:43], s[36:37], 6
	s_add_u32 s10, s58, s42
	s_addc_u32 s11, s59, s43
	s_and_saveexec_b64 s[8:9], s[22:23]
	s_cbranch_execz .LBB0_1656
	s_mov_b64 s[44:45], exec
	v_mbcnt_lo_u32_b32 v146, s44, 0
	v_mbcnt_hi_u32_b32 v146, s45, v146
	v_cmp_eq_u32_e32 vcc, 0, v146
	s_and_b64 s[70:71], exec, vcc
	s_mov_b64 exec, s[70:71]
	s_cbranch_execz .LBB0_1656
	s_bcnt1_i32_b64 s35, s[44:45]
	v_mov_b32_e32 v146, s35
.LBB0_1656:
	s_or_b64 exec, exec, s[8:9]
	v_cndmask_b32_e64 v146, 0, 1, s[24:25]
	v_cmp_ne_u32_e64 s[8:9], 1, v146
	s_andn2_b64 vcc, exec, s[24:25]
	s_cbranch_vccnz .LBB0_1666
	s_branch .LBB0_1666

;     __device__ __forceinline__ void exchange(int e, float (&sv)[2][4], float (&rv)[2][4], const Unit& u, int wr, int wc, int fr, int fq, LAS unsigned char* lds, int wid, int lane) const {
;     ...
;         asm volatile("s_waitcnt vmcnt(0) lgkmcnt(0)" ::: "memory"); __builtin_amdgcn_s_barrier(); asm volatile("" ::: "memory");
;         if (tid < 256) {
;             const float* sl = xbuf + ((size_t)u.pm * 256 + tid) * 4;
;             const float t0 = __hip_atomic_load(sl + 0, __ATOMIC_RELAXED, __HIP_MEMORY_SCOPE_AGENT), t1 = __hip_atomic_load(sl + 1, __ATOMIC_RELAXED, __HIP_MEMORY_SCOPE_AGENT);
.LBB0_1666:
	s_waitcnt lgkmcnt(0)
	s_barrier
	s_and_saveexec_b64 s[44:45], s[6:7]
	s_cbranch_execz .LBB0_1668
	s_lshl_b64 s[10:11], s[36:37], 12
	v_lshl_add_u64 v[146:147], v[138:139], 0, s[10:11]
	v_lshl_or_b32 v232, s34, 8, v222
	v_lshlrev_b32_e32 v232, 2, v232
	global_load_dword v233, v232, s[18:19]
	v_lshl_add_u64 v[250:251], v[146:147], 0, s[10:11]
	v_mov_b32_e32 v249, 0x800000
	v_lshl_add_u32 v248, v222, 4, v249
	v_mov_b32_e32 v249, 0
	v_lshl_add_u64 v[250:251], v[248:249], 0, v[250:251]
	s_mov_b32 s101, 0x4000

;     __device__ __forceinline__ void exchange(int e, float (&sv)[2][4], float (&rv)[2][4], const Unit& u, int wr, int wc, int fr, int fq, LAS unsigned char* lds, int wid, int lane) const {
;     ...
;             const float t0 = __hip_atomic_load(sl + 0, __ATOMIC_RELAXED, __HIP_MEMORY_SCOPE_AGENT), t1 = __hip_atomic_load(sl + 1, __ATOMIC_RELAXED, __HIP_MEMORY_SCOPE_AGENT);
;             const float t2 = __hip_atomic_load(sl + 2, __ATOMIC_RELAXED, __HIP_MEMORY_SCOPE_AGENT), t3 = __hip_atomic_load(sl + 3, __ATOMIC_RELAXED, __HIP_MEMORY_SCOPE_AGENT);
;             Sx[tid] = 1.0f / sqrtf(((t0 + t1) + (t2 + t3)) * (1.0f / 1024.0f) + RMS_EPS);
.Lx_rdy2:
	s_mov_b32 s10, 0xf800000
	v_mov_b32_e32 v148, v236
	v_mov_b32_e32 v150, v238
	v_mov_b32_e32 v149, v240
	v_mov_b32_e32 v151, v242
	v_pk_add_f32 v[146:147], v[148:149], v[150:151]
	s_nop 0
	v_add_f32_e32 v146, v146, v147
	v_fmamk_f32 v146, v146, 0x3a800000, v228
	v_mul_f32_e32 v147, 0x4f800000, v146
	v_cmp_gt_f32_e32 vcc, s10, v146
	s_nop 1
	v_cndmask_b32_e32 v146, v146, v147, vcc
	v_sqrt_f32_e32 v147, v146
	s_nop 0
	v_add_u32_e32 v148, -1, v147
	v_add_u32_e32 v149, 1, v147
	v_fma_f32 v150, -v148, v147, v146
	v_fma_f32 v151, -v149, v147, v146
	v_cmp_ge_f32_e64 s[10:11], 0, v150
	s_nop 1
	v_cndmask_b32_e64 v147, v147, v148, s[10:11]
	v_cmp_lt_f32_e64 s[10:11], 0, v151
	s_nop 1
	v_cndmask_b32_e64 v147, v147, v149, s[10:11]
	v_mul_f32_e32 v148, 0x37800000, v147
	v_cndmask_b32_e32 v147, v147, v148, vcc
	v_cmp_class_f32_e32 vcc, v146, v227
	s_nop 1
	v_cndmask_b32_e32 v146, v147, v146, vcc
	v_div_scale_f32 v147, s[10:11], v146, v146, 1.0
	v_rcp_f32_e32 v148, v147
	v_div_scale_f32 v149, vcc, 1.0, v146, 1.0
	v_fma_f32 v150, -v147, v148, 1.0
	v_fmac_f32_e32 v148, v150, v148
	v_mul_f32_e32 v150, v149, v148
	v_fma_f32 v151, -v147, v150, v149
	v_fmac_f32_e32 v150, v151, v148
	v_fma_f32 v147, -v147, v150, v149
	v_div_fmas_f32 v147, v147, v148, v150
	v_div_fixup_f32 v146, v147, v146, 1.0
	ds_write_b32 v190, v146
	v_mov_b32_e32 v234, 0x21400
	v_lshl_add_u32 v232, v222, 2, v234
	ds_write_b32 v232, v233

; #define LAS __attribute__((address_space(3)))
; __device__ __forceinline__ float xhalf_sum(float x) { auto t = __builtin_amdgcn_permlane32_swap(__float_as_uint(x), __float_as_uint(x), false, false); return __uint_as_float(t[0]) + __uint_as_float(t[1]); }
;     __device__ __forceinline__ void exchange(int e, float (&sv)[2][4], float (&rv)[2][4], const Unit& u, int wr, int wc, int fr, int fq, LAS unsigned char* lds, int wid, int lane) const {
;     ...
;                 float v = sv[ai][m];
;                 { auto t1 = __builtin_amdgcn_permlane16_swap(__float_as_uint(v), __float_as_uint(v), false, false); v = __uint_as_float(t1[0]) + __uint_as_float(t1[1]); }
;                 v = xhalf_sum(v);
;                 if (fq == 0) P[(ai * HALF + wr * 64 + m * 16 + fr) * 4 + wc] = v;
;             }
;         asm volatile("s_waitcnt lgkmcnt(0)" ::: "memory"); __builtin_amdgcn_s_barrier(); asm volatile("" ::: "memory");
;         const int tid = wid * 64 + lane;
;         if (tid < 256) {
;             const f32x4 pp = *(const LAS f32x4*)(P + tid * 4);
;             __hip_atomic_store(xbuf + ((size_t)u.pm * 256 + tid) * 4 + u.pn, (pp[0] + pp[1]) + (pp[2] + pp[3]), __ATOMIC_RELAXED, __HIP_MEMORY_SCOPE_AGENT);
;         }
;         asm volatile("s_waitcnt vmcnt(0)" ::: "memory");
;         if (wid < 4 && lane == 0) __hip_atomic_fetch_add(cnt, 1u, __ATOMIC_RELAXED, __HIP_MEMORY_SCOPE_AGENT);
;         if (wid == 0) {
;             unsigned sp = 0;
;             while ((unsigned)__builtin_amdgcn_readfirstlane(__hip_atomic_load(cnt, __ATOMIC_RELAXED, __HIP_MEMORY_SCOPE_AGENT)) < 16u) { __builtin_amdgcn_s_sleep(2); if (++sp > (1u << 22)) break; }
;             __builtin_amdgcn_fence(__ATOMIC_ACQUIRE, "agent");
;         }
.LBB0_1670:
	v_mov_b32_e32 v154, v195
	s_nop 1
	v_permlane16_swap_b32_e32 v195, v154
	v_add_f32_e32 v154, v195, v154
	v_mov_b32_e32 v155, v154
	s_nop 1
	v_permlane32_swap_b32_e32 v154, v155
	s_and_saveexec_b64 s[10:11], s[4:5]
	v_add_f32_e32 v154, v154, v155
	ds_write_b32 v193, v154
	s_or_b64 exec, exec, s[10:11]
	v_mov_b32_e32 v154, v196
	s_nop 1
	v_permlane16_swap_b32_e32 v196, v154
	v_add_f32_e32 v154, v196, v154
	v_mov_b32_e32 v155, v154
	s_nop 1
	v_permlane32_swap_b32_e32 v154, v155
	s_and_saveexec_b64 s[10:11], s[4:5]
	v_add_f32_e32 v154, v154, v155
	ds_write_b32 v193, v154 offset:256
	s_or_b64 exec, exec, s[10:11]
	v_mov_b32_e32 v154, v197
	s_nop 1
	v_permlane16_swap_b32_e32 v197, v154
	v_add_f32_e32 v154, v197, v154
	v_mov_b32_e32 v155, v154
	s_nop 1
	v_permlane32_swap_b32_e32 v154, v155
	s_and_saveexec_b64 s[10:11], s[4:5]
	v_add_f32_e32 v154, v154, v155
	ds_write_b32 v193, v154 offset:512
	s_or_b64 exec, exec, s[10:11]
	v_mov_b32_e32 v154, v198
	s_nop 1
	v_permlane16_swap_b32_e32 v198, v154
	v_add_f32_e32 v154, v198, v154
	v_mov_b32_e32 v155, v154
	s_nop 1
	v_permlane32_swap_b32_e32 v154, v155
	s_and_saveexec_b64 s[10:11], s[4:5]
	v_add_f32_e32 v154, v154, v155
	ds_write_b32 v193, v154 offset:768
	s_or_b64 exec, exec, s[10:11]
	v_mov_b32_e32 v154, v199
	s_nop 1
	v_permlane16_swap_b32_e32 v199, v154
	v_add_f32_e32 v154, v199, v154
	v_mov_b32_e32 v155, v154
	s_nop 1
	v_permlane32_swap_b32_e32 v154, v155
	s_and_saveexec_b64 s[10:11], s[4:5]
	v_add_f32_e32 v154, v154, v155
	ds_write_b32 v193, v154 offset:2048
	s_or_b64 exec, exec, s[10:11]
	v_mov_b32_e32 v154, v200
	s_nop 1
	v_permlane16_swap_b32_e32 v200, v154
	v_add_f32_e32 v154, v200, v154
	v_mov_b32_e32 v155, v154
	s_nop 1
	v_permlane32_swap_b32_e32 v154, v155
	s_and_saveexec_b64 s[10:11], s[4:5]
	v_add_f32_e32 v154, v154, v155
	ds_write_b32 v193, v154 offset:2304
	s_or_b64 exec, exec, s[10:11]
	v_mov_b32_e32 v154, v158
	s_nop 1
	v_permlane16_swap_b32_e32 v158, v154
	v_add_f32_e32 v154, v158, v154
	v_mov_b32_e32 v155, v154
	s_nop 1
	v_permlane32_swap_b32_e32 v154, v155
	s_and_saveexec_b64 s[10:11], s[4:5]
	v_add_f32_e32 v154, v154, v155
	ds_write_b32 v193, v154 offset:2560
	s_or_b64 exec, exec, s[10:11]
	v_mul_f32_e32 v154, v15, v15
	v_mul_f32_e32 v155, v17, v17
	v_fmac_f32_e32 v154, v14, v14
	v_fmac_f32_e32 v155, v16, v16
	v_add_f32_e32 v154, v154, v155
	v_mul_f32_e32 v155, v11, v11
	v_mul_f32_e32 v156, v13, v13
	v_fmac_f32_e32 v155, v10, v10
	v_fmac_f32_e32 v156, v12, v12
	v_add_f32_e32 v155, v155, v156
	v_add_f32_e32 v154, v154, v155
	v_mul_f32_e32 v155, v7, v7
	v_mul_f32_e32 v156, v9, v9
	v_fmac_f32_e32 v155, v6, v6
	v_fmac_f32_e32 v156, v8, v8
	v_add_f32_e32 v155, v155, v156
	v_mul_f32_e32 v156, v3, v3
	v_mul_f32_e32 v157, v5, v5
	v_fmac_f32_e32 v156, v2, v2
	v_fmac_f32_e32 v157, v4, v4
	v_add_f32_e32 v156, v156, v157
	v_add_f32_e32 v155, v155, v156
	v_add_f32_e32 v154, v154, v155
	v_mov_b32_e32 v155, v154
	s_nop 1
	v_permlane16_swap_b32_e32 v154, v155
	v_add_f32_e32 v154, v154, v155
	v_mov_b32_e32 v155, v154
	s_nop 1
	v_permlane32_swap_b32_e32 v154, v155
	s_and_saveexec_b64 s[10:11], s[4:5]
	v_add_f32_e32 v154, v154, v155
	ds_write_b32 v193, v154 offset:2816
	s_or_b64 exec, exec, s[10:11]
	s_waitcnt lgkmcnt(0)
	s_barrier
	s_and_saveexec_b64 s[10:11], s[6:7]
	s_cbranch_execz .LBB0_1688
	v_add_u32_e32 v154, 0, v189
	v_add_u32_e32 v154, 0x20000, v154
	ds_read_b128 v[154:157], v154
	s_lshl_b64 s[44:45], s[36:37], 12
	v_lshl_add_u64 v[158:159], v[140:141], 0, s[44:45]
	s_mov_b32 s100, s60
	v_lshl_add_u64 v[250:251], v[158:159], 0, s[44:45]
	v_mov_b32_e32 v249, 0x880000
	v_lshl_add_u32 v248, v222, 4, v249
	v_mov_b32_e32 v249, 0
	v_lshl_add_u64 v[250:251], v[248:249], 0, v[250:251]
	s_ashr_i32 s35, s34, 31
	v_lshl_add_u64 v[158:159], s[34:35], 2, v[158:159]
	v_lshl_add_u64 v[248:249], s[34:35], 3, v[250:251]
	s_waitcnt lgkmcnt(0)
	v_mov_b32_e32 v186, v155
	v_mov_b32_e32 v187, v156
	v_mov_b32_e32 v155, v157
	v_pk_add_f32 v[154:155], v[186:187], v[154:155]
	s_nop 0
	v_pk_add_f32 v[154:155], v[154:155], v[154:155] op_sel:[0,1] op_sel_hi:[1,0]
	v_xor_b32_e32 v155, s100, v154
	global_store_dwordx2 v[248:249], v[154:155], off sc1
.LBB0_1688:
	s_or_b64 exec, exec, s[10:11]
	s_add_u32 s10, s60, s42
	s_addc_u32 s11, s61, s43
	s_and_saveexec_b64 s[42:43], s[22:23]
	s_cbranch_execz .LBB0_1691
	s_mov_b64 s[44:45], exec
	v_mbcnt_lo_u32_b32 v154, s44, 0
	v_mbcnt_hi_u32_b32 v154, s45, v154
	v_cmp_eq_u32_e32 vcc, 0, v154
	s_and_b64 s[70:71], exec, vcc
	s_mov_b64 exec, s[70:71]
	s_cbranch_execz .LBB0_1691
	s_bcnt1_i32_b64 s35, s[44:45]
	v_mov_b32_e32 v154, s35
.LBB0_1691:
	s_or_b64 exec, exec, s[42:43]
	s_and_b64 vcc, exec, s[8:9]
	s_cbranch_vccnz .LBB0_1703
	s_branch .LBB0_1703

;     __device__ __forceinline__ void exchange(int e, float (&sv)[2][4], float (&rv)[2][4], const Unit& u, int wr, int wc, int fr, int fq, LAS unsigned char* lds, int wid, int lane) const {
;     ...
;         asm volatile("s_waitcnt vmcnt(0) lgkmcnt(0)" ::: "memory"); __builtin_amdgcn_s_barrier(); asm volatile("" ::: "memory");
;         if (tid < 256) {
;             const float* sl = xbuf + ((size_t)u.pm * 256 + tid) * 4;
;             const float t0 = __hip_atomic_load(sl + 0, __ATOMIC_RELAXED, __HIP_MEMORY_SCOPE_AGENT), t1 = __hip_atomic_load(sl + 1, __ATOMIC_RELAXED, __HIP_MEMORY_SCOPE_AGENT);
.LBB0_1703:
	s_waitcnt lgkmcnt(0)
	s_barrier
	s_and_saveexec_b64 s[10:11], s[6:7]
	s_cbranch_execz .LBB0_1705
	s_lshl_b64 s[8:9], s[36:37], 12
	v_lshl_add_u64 v[154:155], v[140:141], 0, s[8:9]
	v_lshl_add_u64 v[250:251], v[154:155], 0, s[8:9]
	v_mov_b32_e32 v249, 0x880000
	v_lshl_add_u32 v248, v222, 4, v249
	v_mov_b32_e32 v249, 0
	v_lshl_add_u64 v[250:251], v[248:249], 0, v[250:251]
	s_mov_b32 s101, 0x4000

;     __device__ __forceinline__ void exchange(int e, float (&sv)[2][4], float (&rv)[2][4], const Unit& u, int wr, int wc, int fr, int fq, LAS unsigned char* lds, int wid, int lane) const {
;     ...
;             const float t0 = __hip_atomic_load(sl + 0, __ATOMIC_RELAXED, __HIP_MEMORY_SCOPE_AGENT), t1 = __hip_atomic_load(sl + 1, __ATOMIC_RELAXED, __HIP_MEMORY_SCOPE_AGENT);
;             const float t2 = __hip_atomic_load(sl + 2, __ATOMIC_RELAXED, __HIP_MEMORY_SCOPE_AGENT), t3 = __hip_atomic_load(sl + 3, __ATOMIC_RELAXED, __HIP_MEMORY_SCOPE_AGENT);
;             Sx[tid] = 1.0f / sqrtf(((t0 + t1) + (t2 + t3)) * (1.0f / 1024.0f) + RMS_EPS);
.Lx_rdy1:
	s_mov_b32 s8, 0xf800000
	v_mov_b32_e32 v156, v236
	v_mov_b32_e32 v158, v238
	v_mov_b32_e32 v157, v240
	v_mov_b32_e32 v159, v242
	v_pk_add_f32 v[154:155], v[156:157], v[158:159]
	s_nop 0
	v_add_f32_e32 v154, v154, v155
	v_fmamk_f32 v154, v154, 0x3a800000, v228
	v_mul_f32_e32 v155, 0x4f800000, v154
	v_cmp_gt_f32_e32 vcc, s8, v154
	s_nop 1
	v_cndmask_b32_e32 v154, v154, v155, vcc
	v_sqrt_f32_e32 v155, v154
	s_nop 0
	v_add_u32_e32 v156, -1, v155
	v_add_u32_e32 v157, 1, v155
	v_fma_f32 v158, -v156, v155, v154
	v_fma_f32 v159, -v157, v155, v154
	v_cmp_ge_f32_e64 s[8:9], 0, v158
	s_nop 1
	v_cndmask_b32_e64 v155, v155, v156, s[8:9]
	v_cmp_lt_f32_e64 s[8:9], 0, v159
	s_nop 1
	v_cndmask_b32_e64 v155, v155, v157, s[8:9]
	v_mul_f32_e32 v156, 0x37800000, v155
	v_cndmask_b32_e32 v155, v155, v156, vcc
	v_cmp_class_f32_e32 vcc, v154, v227
	s_nop 1
	v_cndmask_b32_e32 v154, v155, v154, vcc
	v_div_scale_f32 v155, s[8:9], v154, v154, 1.0
	v_rcp_f32_e32 v156, v155
	v_div_scale_f32 v157, vcc, 1.0, v154, 1.0
	v_fma_f32 v158, -v155, v156, 1.0
	v_fmac_f32_e32 v156, v158, v156
	v_mul_f32_e32 v158, v157, v156
	v_fma_f32 v159, -v155, v158, v157
	v_fmac_f32_e32 v158, v159, v156
	v_fma_f32 v155, -v155, v158, v157
	v_div_fmas_f32 v155, v155, v156, v158
	v_div_fixup_f32 v154, v155, v154, 1.0
	ds_write_b32 v190, v154
